# wave-sum butterflies: xor-1/2/4/8 steps via DPP moves instead of ds_bpermute round trips (conv LayerNorm, adaLN norm fast path, final norm)
# speedup vs baseline: 1.0017x; 1.0011x over previous
; __device__ __forceinline__ int obid() { int b = (int)blockIdx.x; asm volatile("" : "+s"(b)); return b; }
; __device__ __forceinline__ void ph_norm(const Params& p_, int l, int skip_blocks) {
;     ...
;         for (int pi = (obid() - skip_blocks) * 8 + wave; pi >= 0 && pi < 4096; pi += nw) {
;             const int row = (pi >> 11) * 4096 + (pi & 2047);
;             const f32x4* xr0 = (const f32x4*)(xin + (size_t)row * DM) + lane; const f32x4* xr1 = (const f32x4*)(xin + (size_t)(row + stride) * DM) + lane;
;             const float* md = mod + (size_t)(l * 2 + (row >> 12)) * 6144;
;             f32x4 v0[8], v1[8], ca[8], cb[8];
; #pragma unroll
;             for (int j = 0; j < 8; ++j) { v0[j] = xr0[64 * j]; v1[j] = xr1[64 * j]; }
; #pragma unroll
;             for (int j = 0; j < 8; ++j) { const int col = (64 * j + lane) * 4; ca[j] = *(const f32x4*)(g + col) * (*(const f32x4*)(md + 2048 + col) + 1.f); cb[j] = *(const f32x4*)(md + col); }
.LBB0_204:
	v_and_b32_e32 v0, 0x7ff, v197
	v_and_or_b32 v200, v198, s74, v0
	v_lshlrev_b32_e32 v0, 13, v200
	v_lshl_or_b32 v199, v200, 11, v181
	v_lshl_add_u64 v[2:3], v[98:99], 0, v[0:1]
	v_lshlrev_b32_e32 v0, 2, v199
	v_lshl_add_u64 v[4:5], v[98:99], 0, v[0:1]
	v_lshrrev_b32_e32 v0, 11, v197
	v_or_b32_e32 v0, s3, v0
	v_mul_u32_u24_e32 v0, 0x1800, v0
	global_load_dwordx4 v[62:65], v[2:3], off
	global_load_dwordx4 v[58:61], v[4:5], off
	global_load_dwordx4 v[54:57], v[2:3], off offset:1024
	global_load_dwordx4 v[50:53], v[4:5], off offset:1024
	global_load_dwordx4 v[46:49], v[2:3], off offset:2048
	global_load_dwordx4 v[42:45], v[4:5], off offset:2048
	global_load_dwordx4 v[38:41], v[2:3], off offset:3072
	global_load_dwordx4 v[34:37], v[4:5], off offset:3072
	v_add_co_u32_e32 v2, vcc, s74, v2
	v_lshl_add_u64 v[94:95], v[0:1], 2, s[42:43]
	s_nop 0
	v_addc_co_u32_e32 v3, vcc, 0, v3, vcc
	v_add_co_u32_e32 v4, vcc, s74, v4
	v_lshl_add_u64 v[96:97], v[94:95], 0, s[26:27]
	v_mov_b32_e32 v113, v1
	v_addc_co_u32_e32 v5, vcc, 0, v5, vcc
	v_lshl_add_u64 v[70:71], v[96:97], 0, v[112:113]
	global_load_dwordx4 v[30:33], v[2:3], off
	global_load_dwordx4 v[26:29], v[4:5], off
	global_load_dwordx4 v[22:25], v[2:3], off offset:1024
	global_load_dwordx4 v[18:21], v[4:5], off offset:1024
	global_load_dwordx4 v[14:17], v[2:3], off offset:2048
	global_load_dwordx4 v[10:13], v[4:5], off offset:2048
	global_load_dwordx4 v[6:9], v[2:3], off offset:3072
	s_nop 0
	global_load_dwordx4 v[2:5], v[4:5], off offset:3072
	v_mov_b32_e32 v115, v1
	global_load_dwordx4 v[70:73], v[70:71], off
	v_lshl_add_u64 v[86:87], v[94:95], 0, v[112:113]
	global_load_dwordx4 v[66:69], v[100:101], off
	v_lshl_add_u64 v[74:75], v[96:97], 0, v[114:115]
	v_mov_b32_e32 v117, v1
	v_lshl_add_u64 v[78:79], v[96:97], 0, v[116:117]
	v_mov_b32_e32 v119, v1
	v_lshl_add_u64 v[82:83], v[96:97], 0, v[118:119]
	v_mov_b32_e32 v121, v1
	v_mov_b32_e32 v123, v1
	v_lshl_add_u64 v[90:91], v[96:97], 0, v[122:123]
	v_mov_b32_e32 v125, v1
	v_lshl_add_u64 v[166:167], v[96:97], 0, v[124:125]
	v_mov_b32_e32 v127, v1
	global_load_dwordx4 v[210:213], v[100:101], off offset:1024
	global_load_dwordx4 v[214:217], v[74:75], off
	global_load_dwordx4 v[218:221], v[100:101], off offset:2048
	global_load_dwordx4 v[222:225], v[78:79], off
	global_load_dwordx4 v[226:229], v[100:101], off offset:3072
	global_load_dwordx4 v[230:233], v[82:83], off
	global_load_dwordx4 v[234:237], v[102:103], off
	v_lshl_add_u64 v[250:251], v[96:97], 0, v[120:121]
	global_load_dwordx4 v[238:241], v[250:251], off
	global_load_dwordx4 v[242:245], v[104:105], off
	global_load_dwordx4 v[246:249], v[90:91], off
	v_xor_b32_e32 v119, 8, v178
	s_mov_b32 s12, 0x3a000000
	s_movk_i32 s9, 0xfff
	v_add_u32_e32 v198, s24, v198
	s_waitcnt vmcnt(10)
	v_mul_f32_e32 v0, v30, v30
	v_mul_f32_e32 v113, v31, v31
	v_mul_f32_e32 v115, v32, v32
	v_pk_add_f32 v[72:73], v[72:73], 1.0 op_sel_hi:[1,0]
	v_pk_add_f32 v[70:71], v[70:71], 1.0 op_sel_hi:[1,0]
	v_pk_mul_f32 v[128:129], v[68:69], v[72:73]
	v_pk_mul_f32 v[130:131], v[66:67], v[70:71]
	global_load_dwordx4 v[66:69], v[86:87], off
	v_mul_f32_e32 v117, v33, v33
	s_waitcnt vmcnt(9)
	v_pk_add_f32 v[216:217], v[216:217], 1.0 op_sel_hi:[1,0]
	v_pk_add_f32 v[214:215], v[214:215], 1.0 op_sel_hi:[1,0]
	v_pk_mul_f32 v[132:133], v[212:213], v[216:217]
	v_pk_mul_f32 v[134:135], v[210:211], v[214:215]
	global_load_dwordx4 v[70:73], v[86:87], off offset:1024
	s_nop 0
	s_waitcnt vmcnt(8)
	v_pk_add_f32 v[224:225], v[224:225], 1.0 op_sel_hi:[1,0]
	v_pk_add_f32 v[222:223], v[222:223], 1.0 op_sel_hi:[1,0]
	v_pk_mul_f32 v[136:137], v[220:221], v[224:225]
	v_pk_mul_f32 v[138:139], v[218:219], v[222:223]
	global_load_dwordx4 v[74:77], v[86:87], off offset:2048
	s_nop 0
	s_waitcnt vmcnt(7)
	v_pk_add_f32 v[232:233], v[232:233], 1.0 op_sel_hi:[1,0]
	v_pk_add_f32 v[230:231], v[230:231], 1.0 op_sel_hi:[1,0]
	v_pk_mul_f32 v[140:141], v[228:229], v[232:233]
	v_pk_mul_f32 v[142:143], v[226:227], v[230:231]
	global_load_dwordx4 v[78:81], v[86:87], off offset:3072
	v_lshl_add_u64 v[86:87], v[96:97], 0, v[120:121]
	v_lshl_add_u64 v[96:97], v[96:97], 0, v[126:127]
	s_waitcnt vmcnt(6)
	v_pk_add_f32 v[238:239], v[238:239], 1.0 op_sel_hi:[1,0]
	v_pk_add_f32 v[240:241], v[240:241], 1.0 op_sel_hi:[1,0]
	v_pk_mul_f32 v[160:161], v[234:235], v[238:239]
	v_lshl_add_u64 v[82:83], v[94:95], 0, v[120:121]
	v_pk_mul_f32 v[144:145], v[236:237], v[240:241]
	global_load_dwordx4 v[82:85], v[82:83], off
	s_nop 0
	v_xor_b32_e32 v121, 16, v178
	s_waitcnt vmcnt(5)
	v_pk_add_f32 v[246:247], v[246:247], 1.0 op_sel_hi:[1,0]
	v_pk_add_f32 v[248:249], v[248:249], 1.0 op_sel_hi:[1,0]
	v_pk_mul_f32 v[164:165], v[242:243], v[246:247]
	v_lshl_add_u64 v[86:87], v[94:95], 0, v[122:123]
	v_pk_mul_f32 v[162:163], v[244:245], v[248:249]
	global_load_dwordx4 v[86:89], v[86:87], off
	s_nop 0
	global_load_dwordx4 v[90:93], v[106:107], off
	v_xor_b32_e32 v123, 32, v178
	global_load_dwordx4 v[166:169], v[166:167], off
	s_waitcnt vmcnt(0)
	v_pk_add_f32 v[168:169], v[168:169], 1.0 op_sel_hi:[1,0]
	v_pk_add_f32 v[170:171], v[166:167], 1.0 op_sel_hi:[1,0]
	v_pk_mul_f32 v[166:167], v[92:93], v[168:169]
	v_pk_mul_f32 v[168:169], v[90:91], v[170:171]
	v_lshl_add_u64 v[90:91], v[94:95], 0, v[124:125]
	global_load_dwordx4 v[90:93], v[90:91], off
	s_nop 0
	global_load_dwordx4 v[172:175], v[108:109], off
	global_load_dwordx4 v[202:205], v[96:97], off
	v_lshl_add_u64 v[94:95], v[94:95], 0, v[126:127]
	s_waitcnt vmcnt(0)
; __device__ __forceinline__ float wave_sum(float v) {
; #pragma unroll
;     for (int o = 1; o < 64; o <<= 1) v += __shfl_xor(v, o);
;     return v;
; __device__ __forceinline__ void ph_norm(const Params& p_, int l, int skip_blocks) {
;     ...
;             float s0 = 0.f, s1 = 0.f;
; #pragma unroll
;             for (int j = 0; j < 8; ++j) { s0 += (v0[j][0] * v0[j][0] + v0[j][1] * v0[j][1]) + (v0[j][2] * v0[j][2] + v0[j][3] * v0[j][3]); s1 += (v1[j][0] * v1[j][0] + v1[j][1] * v1[j][1]) + (v1[j][2] * v1[j][2] + v1[j][3] * v1[j][3]); }
;             s0 = wave_sum(s0); s1 = wave_sum(s1);
	v_pk_add_f32 v[176:177], v[202:203], 1.0 op_sel_hi:[1,0]
	v_pk_add_f32 v[96:97], v[204:205], 1.0 op_sel_hi:[1,0]
	v_pk_mul_f32 v[172:173], v[172:173], v[176:177]
	v_mov_b32_e32 v176, v63
	v_mov_b32_e32 v177, v55
	v_pk_mul_f32 v[170:171], v[174:175], v[96:97]
	v_mov_b32_e32 v174, v62
	v_mov_b32_e32 v175, v54
	v_pk_mul_f32 v[176:177], v[176:177], v[176:177]
	v_mov_b32_e32 v202, v65
	v_mov_b32_e32 v203, v57
	v_pk_fma_f32 v[174:175], v[174:175], v[174:175], v[176:177]
	v_mov_b32_e32 v176, v64
	v_mov_b32_e32 v177, v56
	v_pk_mul_f32 v[202:203], v[202:203], v[202:203]
	v_mov_b32_e32 v204, v61
	v_pk_fma_f32 v[176:177], v[176:177], v[176:177], v[202:203]
	v_mov_b32_e32 v202, v59
	v_mov_b32_e32 v203, v51
	v_pk_add_f32 v[174:175], v[174:175], v[176:177]
	v_mov_b32_e32 v176, v58
	v_mov_b32_e32 v177, v50
	v_pk_mul_f32 v[202:203], v[202:203], v[202:203]
	v_mov_b32_e32 v205, v53
	v_pk_fma_f32 v[176:177], v[176:177], v[176:177], v[202:203]
	v_mov_b32_e32 v202, v60
	v_mov_b32_e32 v203, v52
	v_pk_mul_f32 v[204:205], v[204:205], v[204:205]
	v_pk_add_f32 v[174:175], v[174:175], v[174:175] op_sel:[0,1] op_sel_hi:[1,0]
	v_pk_fma_f32 v[202:203], v[202:203], v[202:203], v[204:205]
	v_pk_mul_f32 v[204:205], v[46:47], v[46:47]
	v_pk_add_f32 v[176:177], v[176:177], v[202:203]
	v_pk_mul_f32 v[202:203], v[48:49], v[48:49]
	v_mov_b32_e32 v175, v0
	v_pk_mov_b32 v[206:207], v[204:205], v[202:203] op_sel:[1,0]
	v_mov_b32_e32 v205, v203
	v_pk_add_f32 v[202:203], v[206:207], v[204:205]
	v_pk_mul_f32 v[204:205], v[44:45], v[44:45]
	v_pk_add_f32 v[202:203], v[202:203], v[202:203] op_sel:[0,1] op_sel_hi:[1,0]
	v_pk_mul_f32 v[206:207], v[42:43], v[42:43]
	v_mov_b32_e32 v203, v113
	v_mul_f32_e32 v0, v39, v39
	v_pk_mov_b32 v[208:209], v[206:207], v[204:205] op_sel:[1,0]
	v_mov_b32_e32 v207, v205
	v_pk_add_f32 v[174:175], v[174:175], v[202:203]
	v_pk_fma_f32 v[202:203], v[38:39], v[38:39], v[0:1] op_sel_hi:[1,1,0]
	v_mul_f32_e32 v0, v41, v41
	v_pk_add_f32 v[204:205], v[208:209], v[206:207]
	v_pk_fma_f32 v[206:207], v[40:41], v[40:41], v[0:1] op_sel_hi:[1,1,0]
	v_mov_b32_e32 v203, v115
	v_mov_b32_e32 v207, v117
	v_pk_add_f32 v[202:203], v[202:203], v[206:207]
	v_mul_f32_e32 v0, v26, v26
	v_pk_add_f32 v[174:175], v[174:175], v[202:203]
	v_mul_f32_e32 v113, v27, v27
	v_pk_add_f32 v[176:177], v[176:177], v[176:177] op_sel:[0,1] op_sel_hi:[1,0]
	v_pk_add_f32 v[202:203], v[204:205], v[204:205] op_sel:[0,1] op_sel_hi:[1,0]
	v_mov_b32_e32 v177, v0
	v_mov_b32_e32 v203, v113
	v_mul_f32_e32 v0, v35, v35
	v_pk_add_f32 v[176:177], v[176:177], v[202:203]
	v_pk_fma_f32 v[202:203], v[34:35], v[34:35], v[0:1] op_sel_hi:[1,1,0]
	v_mul_f32_e32 v0, v37, v37
	v_mul_f32_e32 v115, v28, v28
	v_mul_f32_e32 v117, v29, v29
	v_pk_fma_f32 v[204:205], v[36:37], v[36:37], v[0:1] op_sel_hi:[1,1,0]
	v_mov_b32_e32 v203, v115
	v_mov_b32_e32 v205, v117
	v_pk_add_f32 v[202:203], v[202:203], v[204:205]
	v_pk_mul_f32 v[204:205], v[22:23], v[22:23]
	v_pk_add_f32 v[176:177], v[176:177], v[202:203]
	v_pk_mul_f32 v[202:203], v[24:25], v[24:25]
	v_mul_f32_e32 v0, v6, v6
	v_pk_mov_b32 v[206:207], v[204:205], v[202:203] op_sel:[1,0]
	v_mov_b32_e32 v205, v203
	v_pk_add_f32 v[202:203], v[206:207], v[204:205]
	v_mul_f32_e32 v113, v7, v7
	v_pk_add_f32 v[174:175], v[174:175], v[174:175] op_sel:[0,1] op_sel_hi:[1,0]
	v_pk_add_f32 v[202:203], v[202:203], v[202:203] op_sel:[0,1] op_sel_hi:[1,0]
	v_pk_mul_f32 v[204:205], v[20:21], v[20:21]
	v_pk_mul_f32 v[206:207], v[18:19], v[18:19]
	v_mov_b32_e32 v175, v0
	v_mov_b32_e32 v203, v113
	v_mul_f32_e32 v0, v15, v15
	v_pk_mov_b32 v[208:209], v[206:207], v[204:205] op_sel:[1,0]
	v_mov_b32_e32 v207, v205
	v_pk_add_f32 v[174:175], v[174:175], v[202:203]
	v_pk_fma_f32 v[202:203], v[14:15], v[14:15], v[0:1] op_sel_hi:[1,1,0]
	v_mul_f32_e32 v0, v17, v17
	v_pk_add_f32 v[204:205], v[208:209], v[206:207]
	v_mul_f32_e32 v115, v8, v8
	v_mul_f32_e32 v117, v9, v9
	v_pk_fma_f32 v[206:207], v[16:17], v[16:17], v[0:1] op_sel_hi:[1,1,0]
	v_mov_b32_e32 v203, v115
	v_mov_b32_e32 v207, v117
	v_pk_add_f32 v[202:203], v[202:203], v[206:207]
	v_mul_f32_e32 v0, v2, v2
	v_pk_add_f32 v[174:175], v[174:175], v[202:203]
	v_mul_f32_e32 v113, v3, v3
	v_pk_add_f32 v[176:177], v[176:177], v[176:177] op_sel:[0,1] op_sel_hi:[1,0]
	v_pk_add_f32 v[202:203], v[204:205], v[204:205] op_sel:[0,1] op_sel_hi:[1,0]
	v_mov_b32_e32 v177, v0
	v_mov_b32_e32 v203, v113
	v_mul_f32_e32 v0, v11, v11
	v_pk_add_f32 v[176:177], v[176:177], v[202:203]
	v_pk_fma_f32 v[202:203], v[10:11], v[10:11], v[0:1] op_sel_hi:[1,1,0]
	v_mul_f32_e32 v0, v13, v13
	v_mul_f32_e32 v115, v4, v4
	v_mul_f32_e32 v117, v5, v5
	v_pk_fma_f32 v[204:205], v[12:13], v[12:13], v[0:1] op_sel_hi:[1,1,0]
	v_mov_b32_e32 v203, v115
	v_mov_b32_e32 v205, v117
	v_and_b32_e32 v0, 64, v178
	v_pk_add_f32 v[202:203], v[202:203], v[204:205]
	v_add_u32_e32 v0, 64, v0
	v_xor_b32_e32 v113, 1, v178
	v_pk_add_f32 v[176:177], v[176:177], v[202:203]
	v_cmp_lt_i32_e32 vcc, v113, v0
	v_mov_b32_e32 v202, v176
	v_mov_b32_e32 v203, v174
	v_cndmask_b32_e32 v113, v178, v113, vcc
	v_mov_b32_e32 v174, v177
	v_lshlrev_b32_e32 v113, 2, v113
	v_pk_add_f32 v[174:175], v[202:203], v[174:175]
	s_nop 1
	v_mov_b32_dpp v177, v175 quad_perm:[1,0,3,2] row_mask:0xf bank_mask:0xf
	v_mov_b32_dpp v176, v174 quad_perm:[1,0,3,2] row_mask:0xf bank_mask:0xf
	v_xor_b32_e32 v115, 2, v178
	v_cmp_lt_i32_e32 vcc, v115, v0
	v_xor_b32_e32 v117, 4, v178
	global_load_dwordx4 v[94:97], v[94:95], off
	v_cndmask_b32_e32 v115, v178, v115, vcc
	v_lshlrev_b32_e32 v115, 2, v115
	s_waitcnt lgkmcnt(0)
	v_pk_add_f32 v[174:175], v[174:175], v[176:177]
	s_nop 1
	v_mov_b32_dpp v177, v175 quad_perm:[2,3,0,1] row_mask:0xf bank_mask:0xf
	v_mov_b32_dpp v176, v174 quad_perm:[2,3,0,1] row_mask:0xf bank_mask:0xf
	v_cmp_lt_i32_e32 vcc, v117, v0
	s_waitcnt lgkmcnt(0)
; __device__ __forceinline__ unsigned pk2(float lo, float hi) { return f2bf(lo) | (f2bf(hi) << 16); }
; __device__ __forceinline__ void ph_norm(const Params& p_, int l, int skip_blocks) {
;     ...
;             for (int j = 0; j < 8; ++j) { s0 += (v0[j][0] * v0[j][0] + v0[j][1] * v0[j][1]) + (v0[j][2] * v0[j][2] + v0[j][3] * v0[j][3]); s1 += (v1[j][0] * v1[j][0] + v1[j][1] * v1[j][1]) + (v1[j][2] * v1[j][2] + v1[j][3] * v1[j][3]); }
;             s0 = wave_sum(s0); s1 = wave_sum(s1);
;             const float r0 = rsqrtf(s0 * (1.f / DM) + 1e-6f), r1 = rsqrtf(s1 * (1.f / DM) + 1e-6f);
; #pragma unroll
;             for (int j = 0; j < 8; ++j) { const int col = (64 * j + lane) * 4;
;                 const f32x4 o0 = (v0[j] * r0) * ca[j] + cb[j], o1 = (v1[j] * r1) * ca[j] + cb[j]; u32x2 w;
;                 w.x = pk2(o0[0], o0[1]); w.y = pk2(o0[2], o0[3]); *(u32x2*)(h + (size_t)row * DM + col) = w;
;                 w.x = pk2(o1[0], o1[1]); w.y = pk2(o1[2], o1[3]); *(u32x2*)(h + (size_t)(row + stride) * DM + col) = w; }
	v_pk_add_f32 v[174:175], v[174:175], v[176:177]
	v_cndmask_b32_e32 v117, v178, v117, vcc
	v_lshlrev_b32_e32 v117, 2, v117
	s_nop 1
	v_mov_b32_dpp v177, v175 row_half_mirror row_mask:0xf bank_mask:0xf
	v_mov_b32_dpp v176, v174 row_half_mirror row_mask:0xf bank_mask:0xf
	v_cmp_lt_i32_e32 vcc, v119, v0
	s_waitcnt lgkmcnt(0)
	v_pk_add_f32 v[174:175], v[174:175], v[176:177]
	v_cndmask_b32_e32 v119, v178, v119, vcc
	v_lshlrev_b32_e32 v119, 2, v119
	s_nop 1
	v_mov_b32_dpp v177, v175 row_mirror row_mask:0xf bank_mask:0xf
	v_mov_b32_dpp v176, v174 row_mirror row_mask:0xf bank_mask:0xf
	v_cmp_lt_i32_e32 vcc, v121, v0
	s_waitcnt lgkmcnt(0)
	v_pk_add_f32 v[174:175], v[174:175], v[176:177]
	v_cndmask_b32_e32 v121, v178, v121, vcc
	v_lshlrev_b32_e32 v121, 2, v121
	ds_bpermute_b32 v177, v121, v175
	ds_bpermute_b32 v176, v121, v174
	v_cmp_lt_i32_e32 vcc, v123, v0
	s_waitcnt lgkmcnt(0)
	v_pk_add_f32 v[174:175], v[174:175], v[176:177]
	v_cndmask_b32_e32 v0, v178, v123, vcc
	v_lshlrev_b32_e32 v0, 2, v0
	ds_bpermute_b32 v177, v0, v175
	ds_bpermute_b32 v176, v0, v174
	s_waitcnt lgkmcnt(0)
	v_pk_add_f32 v[174:175], v[174:175], v[176:177]
	s_nop 0
	v_pk_fma_f32 v[174:175], v[174:175], s[12:13], v[146:147] op_sel_hi:[1,0,0]
	s_nop 0
	v_mul_f32_e32 v0, 0x4b800000, v175
	v_cmp_gt_f32_e64 s[36:37], s92, v175
	v_cmp_gt_f32_e32 vcc, s92, v174
	s_nop 0
	v_cndmask_b32_e64 v0, v175, v0, s[36:37]
	v_rsq_f32_e32 v0, v0
	s_nop 0
	v_mul_f32_e32 v113, 0x45800000, v0
	v_cndmask_b32_e64 v176, v0, v113, s[36:37]
	v_mul_f32_e32 v0, 0x4b800000, v174
	v_cndmask_b32_e32 v0, v174, v0, vcc
	v_rsq_f32_e32 v0, v0
	v_pk_mul_f32 v[62:63], v[62:63], v[176:177] op_sel_hi:[1,0]
	v_pk_mul_f32 v[64:65], v[64:65], v[176:177] op_sel_hi:[1,0]
	v_pk_fma_f32 v[62:63], v[130:131], v[62:63], v[66:67]
	v_mul_f32_e32 v113, 0x45800000, v0
	v_cndmask_b32_e32 v174, v0, v113, vcc
	v_bfe_u32 v0, v62, 16, 1
	v_add3_u32 v0, v62, v0, s14
	v_bfe_u32 v62, v63, 16, 1
	v_pk_fma_f32 v[64:65], v[128:129], v[64:65], v[68:69]
	v_lshrrev_b32_e32 v0, 16, v0
	v_add3_u32 v62, v63, v62, s14
	v_and_or_b32 v62, v62, s15, v0
	v_bfe_u32 v0, v64, 16, 1
	v_add3_u32 v0, v64, v0, s14
	v_bfe_u32 v63, v65, 16, 1
	v_pk_mul_f32 v[58:59], v[58:59], v[174:175] op_sel_hi:[1,0]
	v_lshrrev_b32_e32 v0, 16, v0
	v_add3_u32 v63, v65, v63, s14
	v_pk_fma_f32 v[58:59], v[130:131], v[58:59], v[66:67]
	v_and_or_b32 v63, v63, s15, v0
	v_lshlrev_b32_e32 v0, 12, v200
	v_lshl_add_u64 v[64:65], v[110:111], 0, v[0:1]
	v_bfe_u32 v0, v58, 16, 1
	v_pk_mul_f32 v[60:61], v[60:61], v[174:175] op_sel_hi:[1,0]
	v_add3_u32 v0, v58, v0, s14
	v_bfe_u32 v58, v59, 16, 1
	v_pk_fma_f32 v[60:61], v[128:129], v[60:61], v[68:69]
	v_lshrrev_b32_e32 v0, 16, v0
	v_add3_u32 v58, v59, v58, s14
	v_and_or_b32 v58, v58, s15, v0
	v_bfe_u32 v0, v60, 16, 1
	v_add3_u32 v0, v60, v0, s14
	v_bfe_u32 v59, v61, 16, 1
	v_lshrrev_b32_e32 v0, 16, v0
	v_add3_u32 v59, v61, v59, s14
	v_pk_mul_f32 v[54:55], v[54:55], v[176:177] op_sel_hi:[1,0]
	v_and_or_b32 v59, v59, s15, v0
	v_lshlrev_b32_e32 v0, 1, v199
	v_pk_fma_f32 v[54:55], v[134:135], v[54:55], v[70:71]
	v_lshl_add_u64 v[60:61], v[110:111], 0, v[0:1]
	v_bfe_u32 v0, v54, 16, 1
	v_pk_mul_f32 v[56:57], v[56:57], v[176:177] op_sel_hi:[1,0]
	v_add3_u32 v0, v54, v0, s14
	v_bfe_u32 v54, v55, 16, 1
	v_pk_fma_f32 v[56:57], v[132:133], v[56:57], v[72:73]
	v_lshrrev_b32_e32 v0, 16, v0
	v_add3_u32 v54, v55, v54, s14
	v_and_or_b32 v54, v54, s15, v0
	v_bfe_u32 v0, v56, 16, 1
	v_pk_mul_f32 v[50:51], v[50:51], v[174:175] op_sel_hi:[1,0]
	v_add3_u32 v0, v56, v0, s14
	v_bfe_u32 v55, v57, 16, 1
	v_pk_fma_f32 v[50:51], v[134:135], v[50:51], v[70:71]
	v_lshrrev_b32_e32 v0, 16, v0
	v_add3_u32 v55, v57, v55, s14
	v_and_or_b32 v55, v55, s15, v0
	v_bfe_u32 v0, v50, 16, 1
	v_pk_mul_f32 v[52:53], v[52:53], v[174:175] op_sel_hi:[1,0]
	v_add3_u32 v0, v50, v0, s14
	v_bfe_u32 v50, v51, 16, 1
	v_pk_fma_f32 v[52:53], v[132:133], v[52:53], v[72:73]
	v_lshrrev_b32_e32 v0, 16, v0
	v_add3_u32 v50, v51, v50, s14
	v_and_or_b32 v50, v50, s15, v0
	v_bfe_u32 v0, v52, 16, 1
	v_add3_u32 v0, v52, v0, s14
	v_bfe_u32 v51, v53, 16, 1
	v_pk_mul_f32 v[46:47], v[46:47], v[176:177] op_sel_hi:[1,0]
	v_lshrrev_b32_e32 v0, 16, v0
	v_add3_u32 v51, v53, v51, s14
	v_pk_fma_f32 v[46:47], v[138:139], v[46:47], v[74:75]
	v_and_or_b32 v51, v51, s15, v0
	v_bfe_u32 v0, v46, 16, 1
	v_pk_mul_f32 v[48:49], v[48:49], v[176:177] op_sel_hi:[1,0]
	v_add3_u32 v0, v46, v0, s14
	v_bfe_u32 v46, v47, 16, 1
	v_pk_fma_f32 v[48:49], v[136:137], v[48:49], v[76:77]
	v_lshrrev_b32_e32 v0, 16, v0
	v_add3_u32 v46, v47, v46, s14
	v_and_or_b32 v46, v46, s15, v0
	v_bfe_u32 v0, v48, 16, 1
	v_pk_mul_f32 v[42:43], v[42:43], v[174:175] op_sel_hi:[1,0]
	v_add3_u32 v0, v48, v0, s14
	v_bfe_u32 v47, v49, 16, 1
	v_pk_fma_f32 v[42:43], v[138:139], v[42:43], v[74:75]
	v_lshrrev_b32_e32 v0, 16, v0
	v_add3_u32 v47, v49, v47, s14
	v_and_or_b32 v47, v47, s15, v0
	v_bfe_u32 v0, v42, 16, 1
	v_pk_mul_f32 v[44:45], v[44:45], v[174:175] op_sel_hi:[1,0]
	v_add3_u32 v0, v42, v0, s14
	v_bfe_u32 v42, v43, 16, 1
	v_pk_fma_f32 v[44:45], v[136:137], v[44:45], v[76:77]
	v_lshrrev_b32_e32 v0, 16, v0
	v_add3_u32 v42, v43, v42, s14
	v_and_or_b32 v42, v42, s15, v0
	v_bfe_u32 v0, v44, 16, 1
	v_add3_u32 v0, v44, v0, s14
	v_bfe_u32 v43, v45, 16, 1
	v_pk_mul_f32 v[38:39], v[38:39], v[176:177] op_sel_hi:[1,0]
	v_lshrrev_b32_e32 v0, 16, v0
	v_add3_u32 v43, v45, v43, s14
	v_pk_fma_f32 v[38:39], v[142:143], v[38:39], v[78:79]
	v_and_or_b32 v43, v43, s15, v0
	v_bfe_u32 v0, v38, 16, 1
	v_pk_mul_f32 v[40:41], v[40:41], v[176:177] op_sel_hi:[1,0]
	v_add3_u32 v0, v38, v0, s14
	v_bfe_u32 v38, v39, 16, 1
	v_pk_fma_f32 v[40:41], v[140:141], v[40:41], v[80:81]
; __device__ __forceinline__ unsigned pk2(float lo, float hi) { return f2bf(lo) | (f2bf(hi) << 16); }
; __device__ __forceinline__ void ph_norm(const Params& p_, int l, int skip_blocks) {
;     ...
;             for (int j = 0; j < 8; ++j) { const int col = (64 * j + lane) * 4;
;                 const f32x4 o0 = (v0[j] * r0) * ca[j] + cb[j], o1 = (v1[j] * r1) * ca[j] + cb[j]; u32x2 w;
;                 w.x = pk2(o0[0], o0[1]); w.y = pk2(o0[2], o0[3]); *(u32x2*)(h + (size_t)row * DM + col) = w;
;                 w.x = pk2(o1[0], o1[1]); w.y = pk2(o1[2], o1[3]); *(u32x2*)(h + (size_t)(row + stride) * DM + col) = w; }
	v_lshrrev_b32_e32 v0, 16, v0
	v_add3_u32 v38, v39, v38, s14
	v_and_or_b32 v38, v38, s15, v0
	v_bfe_u32 v0, v40, 16, 1
	v_pk_mul_f32 v[34:35], v[34:35], v[174:175] op_sel_hi:[1,0]
	v_add3_u32 v0, v40, v0, s14
	v_bfe_u32 v39, v41, 16, 1
	v_pk_fma_f32 v[34:35], v[142:143], v[34:35], v[78:79]
	v_lshrrev_b32_e32 v0, 16, v0
	v_add3_u32 v39, v41, v39, s14
	v_and_or_b32 v39, v39, s15, v0
	v_bfe_u32 v0, v34, 16, 1
	v_pk_mul_f32 v[36:37], v[36:37], v[174:175] op_sel_hi:[1,0]
	v_add3_u32 v0, v34, v0, s14
	v_bfe_u32 v34, v35, 16, 1
	v_pk_fma_f32 v[36:37], v[140:141], v[36:37], v[80:81]
	v_lshrrev_b32_e32 v0, 16, v0
	v_add3_u32 v34, v35, v34, s14
	v_and_or_b32 v34, v34, s15, v0
	v_bfe_u32 v0, v36, 16, 1
	v_add3_u32 v0, v36, v0, s14
	v_bfe_u32 v35, v37, 16, 1
	v_pk_mul_f32 v[30:31], v[30:31], v[176:177] op_sel_hi:[1,0]
	v_lshrrev_b32_e32 v0, 16, v0
	v_add3_u32 v35, v37, v35, s14
	v_pk_fma_f32 v[30:31], v[160:161], v[30:31], v[82:83]
	v_and_or_b32 v35, v35, s15, v0
	v_bfe_u32 v0, v30, 16, 1
	v_pk_mul_f32 v[32:33], v[32:33], v[176:177] op_sel_hi:[1,0]
	v_add3_u32 v0, v30, v0, s14
	v_bfe_u32 v30, v31, 16, 1
	v_pk_fma_f32 v[32:33], v[144:145], v[32:33], v[84:85]
	v_lshrrev_b32_e32 v0, 16, v0
	v_add3_u32 v30, v31, v30, s14
	v_and_or_b32 v30, v30, s15, v0
	v_bfe_u32 v0, v32, 16, 1
	v_pk_mul_f32 v[26:27], v[26:27], v[174:175] op_sel_hi:[1,0]
	v_add3_u32 v0, v32, v0, s14
	v_bfe_u32 v31, v33, 16, 1
	v_pk_fma_f32 v[26:27], v[160:161], v[26:27], v[82:83]
	v_lshrrev_b32_e32 v0, 16, v0
	v_add3_u32 v31, v33, v31, s14
	v_and_or_b32 v31, v31, s15, v0
	v_bfe_u32 v0, v26, 16, 1
	v_pk_mul_f32 v[28:29], v[28:29], v[174:175] op_sel_hi:[1,0]
	v_add3_u32 v0, v26, v0, s14
	v_bfe_u32 v26, v27, 16, 1
	v_pk_fma_f32 v[28:29], v[144:145], v[28:29], v[84:85]
	v_lshrrev_b32_e32 v0, 16, v0
	v_add3_u32 v26, v27, v26, s14
	v_and_or_b32 v26, v26, s15, v0
	v_bfe_u32 v0, v28, 16, 1
	v_add3_u32 v0, v28, v0, s14
	v_bfe_u32 v27, v29, 16, 1
	v_pk_mul_f32 v[22:23], v[22:23], v[176:177] op_sel_hi:[1,0]
	v_lshrrev_b32_e32 v0, 16, v0
	v_add3_u32 v27, v29, v27, s14
	v_pk_fma_f32 v[22:23], v[164:165], v[22:23], v[86:87]
	v_and_or_b32 v27, v27, s15, v0
	v_bfe_u32 v0, v22, 16, 1
	v_pk_mul_f32 v[24:25], v[24:25], v[176:177] op_sel_hi:[1,0]
	v_add3_u32 v0, v22, v0, s14
	v_bfe_u32 v22, v23, 16, 1
	v_pk_fma_f32 v[24:25], v[162:163], v[24:25], v[88:89]
	v_lshrrev_b32_e32 v0, 16, v0
	v_add3_u32 v22, v23, v22, s14
	v_and_or_b32 v22, v22, s15, v0
	v_bfe_u32 v0, v24, 16, 1
	v_pk_mul_f32 v[18:19], v[18:19], v[174:175] op_sel_hi:[1,0]
	v_add3_u32 v0, v24, v0, s14
	v_bfe_u32 v23, v25, 16, 1
	v_pk_fma_f32 v[18:19], v[164:165], v[18:19], v[86:87]
	v_lshrrev_b32_e32 v0, 16, v0
	v_add3_u32 v23, v25, v23, s14
	v_and_or_b32 v23, v23, s15, v0
	v_bfe_u32 v0, v18, 16, 1
	v_pk_mul_f32 v[20:21], v[20:21], v[174:175] op_sel_hi:[1,0]
	v_add3_u32 v0, v18, v0, s14
	v_bfe_u32 v18, v19, 16, 1
	v_pk_fma_f32 v[20:21], v[162:163], v[20:21], v[88:89]
	v_lshrrev_b32_e32 v0, 16, v0
	v_add3_u32 v18, v19, v18, s14
	v_and_or_b32 v18, v18, s15, v0
	v_bfe_u32 v0, v20, 16, 1
	v_add3_u32 v0, v20, v0, s14
	v_bfe_u32 v19, v21, 16, 1
	v_pk_mul_f32 v[14:15], v[14:15], v[176:177] op_sel_hi:[1,0]
	v_lshrrev_b32_e32 v0, 16, v0
	v_add3_u32 v19, v21, v19, s14
	v_pk_fma_f32 v[14:15], v[168:169], v[14:15], v[90:91]
	v_and_or_b32 v19, v19, s15, v0
	v_bfe_u32 v0, v14, 16, 1
	v_pk_mul_f32 v[16:17], v[16:17], v[176:177] op_sel_hi:[1,0]
	v_add3_u32 v0, v14, v0, s14
	v_bfe_u32 v14, v15, 16, 1
	v_pk_fma_f32 v[16:17], v[166:167], v[16:17], v[92:93]
	v_lshrrev_b32_e32 v0, 16, v0
	v_add3_u32 v14, v15, v14, s14
	v_and_or_b32 v14, v14, s15, v0
	v_bfe_u32 v0, v16, 16, 1
	v_pk_mul_f32 v[10:11], v[10:11], v[174:175] op_sel_hi:[1,0]
	v_add3_u32 v0, v16, v0, s14
	v_bfe_u32 v15, v17, 16, 1
	v_pk_fma_f32 v[10:11], v[168:169], v[10:11], v[90:91]
	v_lshrrev_b32_e32 v0, 16, v0
	v_add3_u32 v15, v17, v15, s14
	v_and_or_b32 v15, v15, s15, v0
	v_bfe_u32 v0, v10, 16, 1
	v_pk_mul_f32 v[12:13], v[12:13], v[174:175] op_sel_hi:[1,0]
	v_add3_u32 v0, v10, v0, s14
	v_bfe_u32 v10, v11, 16, 1
	v_pk_fma_f32 v[12:13], v[166:167], v[12:13], v[92:93]
	v_lshrrev_b32_e32 v0, 16, v0
	v_add3_u32 v10, v11, v10, s14
	v_and_or_b32 v10, v10, s15, v0
	v_bfe_u32 v0, v12, 16, 1
	v_add3_u32 v0, v12, v0, s14
	v_bfe_u32 v11, v13, 16, 1
	v_pk_mul_f32 v[6:7], v[6:7], v[176:177] op_sel_hi:[1,0]
	v_lshrrev_b32_e32 v0, 16, v0
	v_add3_u32 v11, v13, v11, s14
	s_waitcnt vmcnt(0)
	v_pk_fma_f32 v[6:7], v[172:173], v[6:7], v[94:95]
	v_and_or_b32 v11, v11, s15, v0
	v_bfe_u32 v0, v6, 16, 1
	v_pk_mul_f32 v[8:9], v[8:9], v[176:177] op_sel_hi:[1,0]
	v_add3_u32 v0, v6, v0, s14
	v_bfe_u32 v6, v7, 16, 1
	v_pk_fma_f32 v[8:9], v[170:171], v[8:9], v[96:97]
	v_lshrrev_b32_e32 v0, 16, v0
	v_add3_u32 v6, v7, v6, s14
	v_and_or_b32 v6, v6, s15, v0
	v_bfe_u32 v0, v8, 16, 1
	v_pk_mul_f32 v[2:3], v[2:3], v[174:175] op_sel_hi:[1,0]
	v_add3_u32 v0, v8, v0, s14
	v_bfe_u32 v7, v9, 16, 1
	v_pk_fma_f32 v[2:3], v[172:173], v[2:3], v[94:95]
	v_lshrrev_b32_e32 v0, 16, v0
	v_add3_u32 v7, v9, v7, s14
	v_and_or_b32 v7, v7, s15, v0
	v_bfe_u32 v0, v2, 16, 1
	v_pk_mul_f32 v[4:5], v[4:5], v[174:175] op_sel_hi:[1,0]
	v_add3_u32 v0, v2, v0, s14
	v_bfe_u32 v2, v3, 16, 1
	v_pk_fma_f32 v[4:5], v[170:171], v[4:5], v[96:97]
	v_lshrrev_b32_e32 v0, 16, v0
	v_add3_u32 v2, v3, v2, s14
	v_and_or_b32 v2, v2, s15, v0
	v_bfe_u32 v0, v4, 16, 1
	v_add3_u32 v0, v4, v0, s14
	v_bfe_u32 v3, v5, 16, 1
	v_lshrrev_b32_e32 v0, 16, v0
	v_add3_u32 v3, v5, v3, s14
	v_and_or_b32 v3, v3, s15, v0
	v_subrev_u32_e32 v0, s10, v197
	v_add_u32_e32 v197, 0x800, v0
	v_cmp_lt_u32_e32 vcc, s9, v197
	s_or_b64 s[46:47], vcc, s[46:47]
	global_store_dwordx2 v[64:65], v[62:63], off
	global_store_dwordx2 v[60:61], v[58:59], off
	global_store_dwordx2 v[64:65], v[54:55], off offset:512
	global_store_dwordx2 v[60:61], v[50:51], off offset:512
	global_store_dwordx2 v[64:65], v[46:47], off offset:1024
	global_store_dwordx2 v[60:61], v[42:43], off offset:1024
	global_store_dwordx2 v[64:65], v[38:39], off offset:1536
	global_store_dwordx2 v[60:61], v[34:35], off offset:1536
	global_store_dwordx2 v[64:65], v[30:31], off offset:2048
	global_store_dwordx2 v[60:61], v[26:27], off offset:2048
	global_store_dwordx2 v[64:65], v[22:23], off offset:2560
	global_store_dwordx2 v[60:61], v[18:19], off offset:2560
	global_store_dwordx2 v[64:65], v[14:15], off offset:3072
	global_store_dwordx2 v[60:61], v[10:11], off offset:3072
	global_store_dwordx2 v[64:65], v[6:7], off offset:3584
	global_store_dwordx2 v[60:61], v[2:3], off offset:3584
	s_andn2_b64 exec, exec, s[46:47]
	s_cbranch_execnz .LBB0_204

; __device__ __forceinline__ void conv_task(const Params& p_, int l, int task, unsigned char* lds) {
;     ...
;     float w[31];
; #pragma unroll
;     for (int k = 0; k < 31; ++k) w[k] = p.conv_w[(size_t)(l * 31 + k) * DG + tid];
;     const float cb = p.conv_b[l * DG + tid];
;     __syncthreads();
;     { float y[16];
; #pragma unroll
;       for (int t = 0; t < 16; ++t) y[t] = cb;
; #pragma unroll
;       for (int j = 0; j < 46; ++j) { const float u = us[j * 512 + tid];
.LBB0_426:
	s_or_b64 exec, exec, s[38:39]
	s_waitcnt vmcnt(0) lgkmcnt(0)
	v_mov_b32_e32 v2, s56
	v_mov_b32_e32 v3, s57
	v_ashrrev_i32_e32 v55, 31, v54
	v_lshl_add_u64 v[2:3], v[54:55], 2, v[2:3]
	v_lshl_add_u64 v[2:3], s[24:25], 2, v[2:3]
	v_add_co_u32_e32 v6, vcc, s74, v2
	s_movk_i32 s6, 0x5000
	s_nop 0
	v_addc_co_u32_e32 v7, vcc, 0, v3, vcc
	v_add_co_u32_e32 v8, vcc, s97, v2
	global_load_dword v33, v[2:3], off
	global_load_dword v0, v[2:3], off offset:2048
	global_load_dword v32, v[6:7], off offset:2048
	v_addc_co_u32_e32 v9, vcc, 0, v3, vcc
	v_add_co_u32_e32 v6, vcc, s5, v2
	v_add_u32_e32 v24, s3, v54
	s_nop 0
	v_addc_co_u32_e32 v7, vcc, 0, v3, vcc
	v_add_co_u32_e32 v10, vcc, s7, v2
	v_mov_b32_e32 v4, s58
	s_nop 0
	v_addc_co_u32_e32 v11, vcc, 0, v3, vcc
	v_add_co_u32_e32 v12, vcc, s6, v2
	s_movk_i32 s6, 0x7000
	s_nop 0
	v_addc_co_u32_e32 v13, vcc, 0, v3, vcc
	v_add_co_u32_e32 v14, vcc, s93, v2
	v_mov_b32_e32 v5, s59
	s_nop 0
	v_addc_co_u32_e32 v15, vcc, 0, v3, vcc
	global_load_dword v41, v[8:9], off offset:-4096
	global_load_dword v40, v[8:9], off
	global_load_dword v39, v[8:9], off offset:2048
	global_load_dword v38, v[10:11], off offset:-4096
	global_load_dword v36, v[10:11], off
	global_load_dword v35, v[10:11], off offset:2048
	global_load_dword v37, v[14:15], off offset:-4096
	global_load_dword v34, v[14:15], off
	v_add_co_u32_e32 v8, vcc, s6, v2
	s_mov_b32 s6, 0x8000
	s_nop 0
	v_addc_co_u32_e32 v9, vcc, 0, v3, vcc
	v_add_co_u32_e32 v10, vcc, s6, v2
	s_mov_b32 s6, 0x9000
	s_nop 0
	v_addc_co_u32_e32 v11, vcc, 0, v3, vcc
	v_add_co_u32_e32 v16, vcc, s6, v2
	s_mov_b32 s6, 0xb000
	s_nop 0
	v_addc_co_u32_e32 v17, vcc, 0, v3, vcc
	v_add_co_u32_e32 v18, vcc, s96, v2
	v_ashrrev_i32_e32 v25, 31, v24
	s_nop 0
	v_addc_co_u32_e32 v19, vcc, 0, v3, vcc
	v_add_co_u32_e32 v20, vcc, s6, v2
	s_mov_b32 s6, 0xc000
	s_nop 0
	v_addc_co_u32_e32 v21, vcc, 0, v3, vcc
	v_add_co_u32_e32 v22, vcc, s6, v2
	v_lshl_add_u64 v[4:5], v[24:25], 2, v[4:5]
	s_nop 0
	v_addc_co_u32_e32 v23, vcc, 0, v3, vcc
	global_load_dword v42, v[4:5], off
	global_load_dword v61, v[14:15], off offset:2048
	global_load_dword v57, v[10:11], off offset:-4096
	global_load_dword v52, v[10:11], off
	global_load_dword v50, v[10:11], off offset:2048
	global_load_dword v48, v[18:19], off offset:-4096
	global_load_dword v45, v[18:19], off
	global_load_dword v44, v[18:19], off offset:2048
	global_load_dword v43, v[22:23], off offset:-4096
	global_load_dword v65, v[6:7], off offset:2048
	global_load_dword v64, v[12:13], off offset:2048
	global_load_dword v63, v[8:9], off offset:2048
	global_load_dword v58, v[16:17], off offset:2048
	global_load_dword v46, v[20:21], off offset:2048
	s_mov_b32 s6, 0xd000
	v_add_co_u32_e32 v4, vcc, s6, v2
	s_mov_b32 s6, 0xe000
	s_nop 0
	v_addc_co_u32_e32 v5, vcc, 0, v3, vcc
	v_add_co_u32_e32 v6, vcc, s6, v2
	s_mov_b32 s6, 0xf000
	s_nop 0
	v_addc_co_u32_e32 v7, vcc, 0, v3, vcc
	global_load_dword v47, v[4:5], off offset:2048
	global_load_dword v62, v[22:23], off
	global_load_dword v59, v[22:23], off offset:2048
	global_load_dword v53, v[6:7], off offset:-4096
	global_load_dword v51, v[6:7], off
	global_load_dword v49, v[6:7], off offset:2048
	v_add_co_u32_e32 v2, vcc, s6, v2
	v_lshlrev_b32_e32 v60, 2, v54
	s_nop 0
	v_addc_co_u32_e32 v3, vcc, 0, v3, vcc
	global_load_dword v55, v[2:3], off
	v_add_u32_e32 v66, 0, v60
	s_barrier
	ds_read2st64_b32 v[80:81], v66 offset1:8
	ds_read2st64_b32 v[30:31], v66 offset0:16 offset1:24
	ds_read2st64_b32 v[28:29], v66 offset0:32 offset1:40
	ds_read2st64_b32 v[26:27], v66 offset0:48 offset1:56
	ds_read2st64_b32 v[24:25], v66 offset0:64 offset1:72
	ds_read2st64_b32 v[22:23], v66 offset0:80 offset1:88
	ds_read2st64_b32 v[20:21], v66 offset0:96 offset1:104
	ds_read2st64_b32 v[18:19], v66 offset0:112 offset1:120
	ds_read2st64_b32 v[16:17], v66 offset0:128 offset1:136
	ds_read2st64_b32 v[14:15], v66 offset0:144 offset1:152
	ds_read2st64_b32 v[12:13], v66 offset0:160 offset1:168
	ds_read2st64_b32 v[10:11], v66 offset0:176 offset1:184
	ds_read2st64_b32 v[8:9], v66 offset0:192 offset1:200
	ds_read2st64_b32 v[6:7], v66 offset0:208 offset1:216
	ds_read2st64_b32 v[4:5], v66 offset0:224 offset1:232
	ds_read2st64_b32 v[2:3], v66 offset0:240 offset1:248
	v_add_u32_e32 v67, 0x10000, v66
	v_add_u32_e32 v68, 0x10800, v66
	v_add_u32_e32 v69, 0x11000, v66
	v_add_u32_e32 v70, 0x11800, v66
	v_add_u32_e32 v74, 0x12000, v66
	v_add_u32_e32 v76, 0x12800, v66
	v_add_u32_e32 v77, 0x13000, v66
	v_add_u32_e32 v78, 0x13800, v66
	ds_read_b32 v75, v67
	ds_read_b32 v73, v68
	ds_read_b32 v72, v69
	ds_read_b32 v71, v70
	ds_read_b32 v70, v74
	ds_read_b32 v69, v76
	ds_read_b32 v68, v77
	ds_read_b32 v67, v78
	v_add_u32_e32 v74, 0x14000, v66
	v_add_u32_e32 v76, 0x14800, v66
	v_add_u32_e32 v77, 0x15000, v66
	v_add_u32_e32 v82, 0x15800, v66
	v_add_u32_e32 v83, 0x16000, v66
	v_add_u32_e32 v66, 0x16800, v66
	ds_read_b32 v79, v74
	ds_read_b32 v78, v76
	ds_read_b32 v77, v77
	ds_read_b32 v76, v82
	ds_read_b32 v74, v83
	ds_read_b32 v82, v66
	v_readlane_b32 s6, v255, 25
	s_add_i32 s26, s26, -1
	s_cmp_eq_u32 s26, 0
	s_cselect_b64 s[38:39], -1, 0
	s_add_u32 s40, s50, 0x12520000
	s_addc_u32 s41, s51, 0
	s_add_i32 s27, s27, 0x100
	s_max_u32 s27, s27, 0x200
	s_mov_b32 s9, s27
	s_mov_b64 s[48:49], 0
	s_waitcnt vmcnt(20) lgkmcnt(14)
; __device__ __forceinline__ void conv_task(const Params& p_, int l, int task, unsigned char* lds) {
;     ...
;     { float y[16];
; #pragma unroll
;       for (int t = 0; t < 16; ++t) y[t] = cb;
; #pragma unroll
;       for (int j = 0; j < 46; ++j) { const float u = us[j * 512 + tid];
; #pragma unroll
;           for (int t = 0; t < 16; ++t) { const int k = j - t; if (k >= 0 && k < 31) y[t] += w[k] * u; } }
	v_fma_f32 v80, v33, v80, v42
	v_fmac_f32_e32 v80, v0, v81
	v_fma_f32 v81, v33, v81, v42
	v_fmac_f32_e32 v80, v41, v30
	v_fmac_f32_e32 v81, v0, v30
	v_fma_f32 v30, v33, v30, v42
	v_fmac_f32_e32 v80, v32, v31
	v_fmac_f32_e32 v81, v41, v31
	v_fmac_f32_e32 v30, v0, v31
	v_fma_f32 v31, v33, v31, v42
	v_fmac_f32_e32 v80, v40, v28
	v_fmac_f32_e32 v81, v32, v28
	v_fmac_f32_e32 v30, v41, v28
	v_fmac_f32_e32 v31, v0, v28
	v_fma_f32 v28, v33, v28, v42
	v_fmac_f32_e32 v80, v39, v29
	v_fmac_f32_e32 v81, v40, v29
	v_fmac_f32_e32 v30, v32, v29
	v_fmac_f32_e32 v31, v41, v29
	v_fmac_f32_e32 v28, v0, v29
	v_fma_f32 v29, v33, v29, v42
	v_fmac_f32_e32 v80, v38, v26
	v_fmac_f32_e32 v81, v39, v26
	v_fmac_f32_e32 v30, v40, v26
	v_fmac_f32_e32 v31, v32, v26
	v_fmac_f32_e32 v28, v41, v26
	v_fmac_f32_e32 v29, v0, v26
	v_fma_f32 v26, v33, v26, v42
	s_waitcnt vmcnt(11)
	v_fmac_f32_e32 v80, v65, v27
	v_fmac_f32_e32 v81, v38, v27
	v_fmac_f32_e32 v30, v39, v27
	v_fmac_f32_e32 v31, v40, v27
	v_fmac_f32_e32 v28, v32, v27
	v_fmac_f32_e32 v29, v41, v27
	v_fmac_f32_e32 v26, v0, v27
	v_fma_f32 v27, v33, v27, v42
	v_fmac_f32_e32 v80, v36, v24
	v_fmac_f32_e32 v81, v65, v24
	v_fmac_f32_e32 v30, v38, v24
	v_fmac_f32_e32 v31, v39, v24
	v_fmac_f32_e32 v28, v40, v24
	v_fmac_f32_e32 v29, v32, v24
	v_fmac_f32_e32 v26, v41, v24
	v_fmac_f32_e32 v27, v0, v24
	v_fma_f32 v24, v33, v24, v42
	v_fmac_f32_e32 v80, v35, v25
	v_fmac_f32_e32 v81, v36, v25
	v_fmac_f32_e32 v30, v65, v25
	v_fmac_f32_e32 v31, v38, v25
	v_fmac_f32_e32 v28, v39, v25
	v_fmac_f32_e32 v29, v40, v25
	v_fmac_f32_e32 v26, v32, v25
	v_fmac_f32_e32 v27, v41, v25
	v_fmac_f32_e32 v24, v0, v25
	v_fma_f32 v25, v33, v25, v42
	v_fmac_f32_e32 v80, v37, v22
	v_fmac_f32_e32 v81, v35, v22
	v_fmac_f32_e32 v30, v36, v22
	v_fmac_f32_e32 v31, v65, v22
	v_fmac_f32_e32 v28, v38, v22
	v_fmac_f32_e32 v29, v39, v22
	v_fmac_f32_e32 v26, v40, v22
	v_fmac_f32_e32 v27, v32, v22
	v_fmac_f32_e32 v24, v41, v22
	v_fmac_f32_e32 v25, v0, v22
	v_fma_f32 v22, v33, v22, v42
	s_waitcnt vmcnt(10)
	v_fmac_f32_e32 v80, v64, v23
	v_fmac_f32_e32 v81, v37, v23
	v_fmac_f32_e32 v30, v35, v23
	v_fmac_f32_e32 v31, v36, v23
	v_fmac_f32_e32 v28, v65, v23
	v_fmac_f32_e32 v29, v38, v23
	v_fmac_f32_e32 v26, v39, v23
	v_fmac_f32_e32 v27, v40, v23
	v_fmac_f32_e32 v24, v32, v23
	v_fmac_f32_e32 v25, v41, v23
	v_fmac_f32_e32 v22, v0, v23
	v_fma_f32 v23, v33, v23, v42
	v_fmac_f32_e32 v80, v34, v20
	v_fmac_f32_e32 v81, v64, v20
	v_fmac_f32_e32 v30, v37, v20
	v_fmac_f32_e32 v31, v35, v20
	v_fmac_f32_e32 v28, v36, v20
	v_fmac_f32_e32 v29, v65, v20
	v_fmac_f32_e32 v26, v38, v20
	v_fmac_f32_e32 v27, v39, v20
	v_fmac_f32_e32 v24, v40, v20
	v_fmac_f32_e32 v25, v32, v20
	v_fmac_f32_e32 v22, v41, v20
	v_fmac_f32_e32 v23, v0, v20
	v_fma_f32 v20, v33, v20, v42
	v_fma_f32 v66, v33, v19, v42
	v_fmac_f32_e32 v80, v61, v21
	v_fmac_f32_e32 v81, v34, v21
	v_fmac_f32_e32 v30, v64, v21
	v_fmac_f32_e32 v31, v37, v21
	v_fmac_f32_e32 v28, v35, v21
	v_fmac_f32_e32 v29, v36, v21
	v_fmac_f32_e32 v26, v65, v21
	v_fmac_f32_e32 v27, v38, v21
	v_fmac_f32_e32 v24, v39, v21
	v_fmac_f32_e32 v25, v40, v21
	v_fmac_f32_e32 v22, v32, v21
	v_fmac_f32_e32 v23, v41, v21
	v_fmac_f32_e32 v20, v0, v21
	v_fma_f32 v21, v33, v21, v42
	v_fmac_f32_e32 v42, v33, v18
	v_fmac_f32_e32 v66, v0, v16
	v_fmac_f32_e32 v21, v0, v18
	v_fmac_f32_e32 v42, v0, v19
	v_fmac_f32_e32 v66, v41, v17
	v_fmac_f32_e32 v20, v41, v18
	v_fmac_f32_e32 v21, v41, v19
	v_fmac_f32_e32 v42, v41, v16
	v_fmac_f32_e32 v66, v32, v14
	v_fmac_f32_e32 v80, v57, v18
	v_fmac_f32_e32 v81, v61, v18
	v_fmac_f32_e32 v30, v34, v18
	v_fmac_f32_e32 v31, v64, v18
	v_fmac_f32_e32 v28, v37, v18
	v_fmac_f32_e32 v29, v35, v18
	v_fmac_f32_e32 v26, v36, v18
	v_fmac_f32_e32 v27, v65, v18
	v_fmac_f32_e32 v24, v38, v18
	v_fmac_f32_e32 v25, v39, v18
	v_fmac_f32_e32 v22, v40, v18
	v_fmac_f32_e32 v23, v32, v18
	v_fmac_f32_e32 v20, v32, v19
	v_fmac_f32_e32 v21, v32, v16
	v_fmac_f32_e32 v42, v32, v17
	v_fmac_f32_e32 v66, v40, v15
	s_waitcnt vmcnt(9)
	v_fmac_f32_e32 v80, v63, v19
	v_fmac_f32_e32 v81, v57, v19
	v_fmac_f32_e32 v30, v61, v19
	v_fmac_f32_e32 v31, v34, v19
	v_fmac_f32_e32 v28, v64, v19
	v_fmac_f32_e32 v29, v37, v19
	v_fmac_f32_e32 v26, v35, v19
	v_fmac_f32_e32 v27, v36, v19
	v_fmac_f32_e32 v24, v65, v19
	v_fmac_f32_e32 v25, v38, v19
	v_fmac_f32_e32 v22, v39, v19
	v_fmac_f32_e32 v23, v40, v19
	v_fmac_f32_e32 v20, v40, v16
	v_fmac_f32_e32 v21, v40, v17
	v_fmac_f32_e32 v42, v40, v14
	v_fmac_f32_e32 v66, v39, v12
	v_fmac_f32_e32 v80, v52, v16
	v_fmac_f32_e32 v81, v63, v16
	v_fmac_f32_e32 v30, v57, v16
	v_fmac_f32_e32 v31, v61, v16
	v_fmac_f32_e32 v28, v34, v16
	v_fmac_f32_e32 v29, v64, v16
	v_fmac_f32_e32 v26, v37, v16
	v_fmac_f32_e32 v27, v35, v16
	v_fmac_f32_e32 v24, v36, v16
	v_fmac_f32_e32 v25, v65, v16
	v_fmac_f32_e32 v22, v38, v16
	v_fmac_f32_e32 v23, v39, v16
	v_fmac_f32_e32 v20, v39, v17
	v_fmac_f32_e32 v21, v39, v14
	v_fmac_f32_e32 v42, v39, v15
	v_fmac_f32_e32 v66, v38, v13
	v_fmac_f32_e32 v80, v50, v17
	v_fmac_f32_e32 v81, v52, v17
	v_fmac_f32_e32 v30, v63, v17
	v_fmac_f32_e32 v31, v57, v17
	v_fmac_f32_e32 v28, v61, v17
	v_fmac_f32_e32 v29, v34, v17
	v_fmac_f32_e32 v26, v64, v17
	v_fmac_f32_e32 v27, v37, v17
	v_fmac_f32_e32 v24, v35, v17
	v_fmac_f32_e32 v25, v36, v17
	v_fmac_f32_e32 v22, v65, v17
	v_fmac_f32_e32 v23, v38, v17
	v_fmac_f32_e32 v20, v38, v14
	v_fmac_f32_e32 v21, v38, v15
	v_fmac_f32_e32 v42, v38, v12
	v_fmac_f32_e32 v66, v65, v10
	v_fmac_f32_e32 v80, v48, v14
	v_fmac_f32_e32 v81, v50, v14
	v_fmac_f32_e32 v30, v52, v14
	v_fmac_f32_e32 v31, v63, v14
	v_fmac_f32_e32 v28, v57, v14
	v_fmac_f32_e32 v29, v61, v14
	v_fmac_f32_e32 v26, v34, v14
	v_fmac_f32_e32 v27, v64, v14
	v_fmac_f32_e32 v24, v37, v14
	v_fmac_f32_e32 v25, v35, v14
	v_fmac_f32_e32 v22, v36, v14
	v_fmac_f32_e32 v23, v65, v14
	v_fmac_f32_e32 v20, v65, v15
	v_fmac_f32_e32 v21, v65, v12
	v_fmac_f32_e32 v42, v65, v13
	v_fmac_f32_e32 v66, v36, v11
	s_waitcnt vmcnt(8)
; __device__ __forceinline__ void conv_task(const Params& p_, int l, int task, unsigned char* lds) {
;     ...
;       for (int j = 0; j < 46; ++j) { const float u = us[j * 512 + tid];
; #pragma unroll
;           for (int t = 0; t < 16; ++t) { const int k = j - t; if (k >= 0 && k < 31) y[t] += w[k] * u; } }
	v_fmac_f32_e32 v80, v58, v15
	v_fmac_f32_e32 v81, v48, v15
	v_fmac_f32_e32 v30, v50, v15
	v_fmac_f32_e32 v31, v52, v15
	v_fmac_f32_e32 v28, v63, v15
	v_fmac_f32_e32 v29, v57, v15
	v_fmac_f32_e32 v26, v61, v15
	v_fmac_f32_e32 v27, v34, v15
	v_fmac_f32_e32 v24, v64, v15
	v_fmac_f32_e32 v25, v37, v15
	v_fmac_f32_e32 v22, v35, v15
	v_fmac_f32_e32 v23, v36, v15
	v_fmac_f32_e32 v20, v36, v12
	v_fmac_f32_e32 v21, v36, v13
	v_fmac_f32_e32 v42, v36, v10
	v_fmac_f32_e32 v66, v35, v8
	v_fmac_f32_e32 v80, v45, v12
	v_fmac_f32_e32 v81, v58, v12
	v_fmac_f32_e32 v30, v48, v12
	v_fmac_f32_e32 v31, v50, v12
	v_fmac_f32_e32 v28, v52, v12
	v_fmac_f32_e32 v29, v63, v12
	v_fmac_f32_e32 v26, v57, v12
	v_fmac_f32_e32 v27, v61, v12
	v_fmac_f32_e32 v24, v34, v12
	v_fmac_f32_e32 v25, v64, v12
	v_fmac_f32_e32 v22, v37, v12
	v_fmac_f32_e32 v23, v35, v12
	v_fmac_f32_e32 v20, v35, v13
	v_fmac_f32_e32 v21, v35, v10
	v_fmac_f32_e32 v42, v35, v11
	v_fmac_f32_e32 v66, v37, v9
	v_fmac_f32_e32 v80, v44, v13
	v_fmac_f32_e32 v81, v45, v13
	v_fmac_f32_e32 v30, v58, v13
	v_fmac_f32_e32 v31, v48, v13
	v_fmac_f32_e32 v28, v50, v13
	v_fmac_f32_e32 v29, v52, v13
	v_fmac_f32_e32 v26, v63, v13
	v_fmac_f32_e32 v27, v57, v13
	v_fmac_f32_e32 v24, v61, v13
	v_fmac_f32_e32 v25, v34, v13
	v_fmac_f32_e32 v22, v64, v13
	v_fmac_f32_e32 v23, v37, v13
	v_fmac_f32_e32 v20, v37, v10
	v_fmac_f32_e32 v21, v37, v11
	v_fmac_f32_e32 v42, v37, v8
	v_fmac_f32_e32 v66, v64, v6
	v_fmac_f32_e32 v80, v43, v10
	v_fmac_f32_e32 v81, v44, v10
	v_fmac_f32_e32 v30, v45, v10
	v_fmac_f32_e32 v31, v58, v10
	v_fmac_f32_e32 v28, v48, v10
	v_fmac_f32_e32 v29, v50, v10
	v_fmac_f32_e32 v26, v52, v10
	v_fmac_f32_e32 v27, v63, v10
	v_fmac_f32_e32 v24, v57, v10
	v_fmac_f32_e32 v25, v61, v10
	v_fmac_f32_e32 v22, v34, v10
	v_fmac_f32_e32 v23, v64, v10
	v_fmac_f32_e32 v20, v64, v11
	v_fmac_f32_e32 v21, v64, v8
	v_fmac_f32_e32 v42, v64, v9
	v_fmac_f32_e32 v66, v34, v7
	s_waitcnt vmcnt(7)
	v_fmac_f32_e32 v80, v46, v11
	v_fmac_f32_e32 v81, v43, v11
	v_fmac_f32_e32 v30, v44, v11
	v_fmac_f32_e32 v31, v45, v11
	v_fmac_f32_e32 v28, v58, v11
	v_fmac_f32_e32 v29, v48, v11
	v_fmac_f32_e32 v26, v50, v11
	v_fmac_f32_e32 v27, v52, v11
	v_fmac_f32_e32 v24, v63, v11
	v_fmac_f32_e32 v25, v57, v11
	v_fmac_f32_e32 v22, v61, v11
	v_fmac_f32_e32 v23, v34, v11
	v_fmac_f32_e32 v20, v34, v8
	v_fmac_f32_e32 v21, v34, v9
	v_fmac_f32_e32 v42, v34, v6
	v_fmac_f32_e32 v66, v61, v4
	s_waitcnt vmcnt(5)
	v_fmac_f32_e32 v80, v62, v8
	v_fmac_f32_e32 v81, v46, v8
	v_fmac_f32_e32 v30, v43, v8
	v_fmac_f32_e32 v31, v44, v8
	v_fmac_f32_e32 v28, v45, v8
	v_fmac_f32_e32 v29, v58, v8
	v_fmac_f32_e32 v26, v48, v8
	v_fmac_f32_e32 v27, v50, v8
	v_fmac_f32_e32 v24, v52, v8
	v_fmac_f32_e32 v25, v63, v8
	v_fmac_f32_e32 v22, v57, v8
	v_fmac_f32_e32 v23, v61, v8
	v_fmac_f32_e32 v20, v61, v9
	v_fmac_f32_e32 v21, v61, v6
	v_fmac_f32_e32 v42, v61, v7
	v_fmac_f32_e32 v66, v57, v5
	s_waitcnt vmcnt(4)
	v_fmac_f32_e32 v80, v59, v9
	v_fmac_f32_e32 v81, v62, v9
	v_fmac_f32_e32 v30, v46, v9
	v_fmac_f32_e32 v31, v43, v9
	v_fmac_f32_e32 v28, v44, v9
	v_fmac_f32_e32 v29, v45, v9
	v_fmac_f32_e32 v26, v58, v9
	v_fmac_f32_e32 v27, v48, v9
	v_fmac_f32_e32 v24, v50, v9
	v_fmac_f32_e32 v25, v52, v9
	v_fmac_f32_e32 v22, v63, v9
	v_fmac_f32_e32 v23, v57, v9
	v_fmac_f32_e32 v20, v57, v6
	v_fmac_f32_e32 v21, v57, v7
	v_fmac_f32_e32 v42, v57, v4
	v_fmac_f32_e32 v66, v63, v2
	s_waitcnt vmcnt(3)
	v_fmac_f32_e32 v80, v53, v6
	v_fmac_f32_e32 v81, v59, v6
	v_fmac_f32_e32 v30, v62, v6
	v_fmac_f32_e32 v31, v46, v6
	v_fmac_f32_e32 v28, v43, v6
	v_fmac_f32_e32 v29, v44, v6
	v_fmac_f32_e32 v26, v45, v6
	v_fmac_f32_e32 v27, v58, v6
	v_fmac_f32_e32 v24, v48, v6
	v_fmac_f32_e32 v25, v50, v6
	v_fmac_f32_e32 v22, v52, v6
	v_fmac_f32_e32 v23, v63, v6
	v_fmac_f32_e32 v20, v63, v7
	v_fmac_f32_e32 v21, v63, v4
	v_fmac_f32_e32 v42, v63, v5
	v_fmac_f32_e32 v66, v52, v3
	v_fmac_f32_e32 v80, v47, v7
	v_fmac_f32_e32 v81, v53, v7
	v_fmac_f32_e32 v30, v59, v7
	v_fmac_f32_e32 v31, v62, v7
	v_fmac_f32_e32 v28, v46, v7
	v_fmac_f32_e32 v29, v43, v7
	v_fmac_f32_e32 v26, v44, v7
	v_fmac_f32_e32 v27, v45, v7
	v_fmac_f32_e32 v24, v58, v7
	v_fmac_f32_e32 v25, v48, v7
	v_fmac_f32_e32 v22, v50, v7
	v_fmac_f32_e32 v23, v52, v7
	v_fmac_f32_e32 v20, v52, v4
	v_fmac_f32_e32 v21, v52, v5
	v_fmac_f32_e32 v42, v52, v2
	s_waitcnt lgkmcnt(13)
	v_fmac_f32_e32 v66, v50, v75
	s_waitcnt vmcnt(2)
	v_fmac_f32_e32 v80, v51, v4
	v_fmac_f32_e32 v81, v47, v4
	v_fmac_f32_e32 v30, v53, v4
	v_fmac_f32_e32 v31, v59, v4
	v_fmac_f32_e32 v28, v62, v4
	v_fmac_f32_e32 v29, v46, v4
	v_fmac_f32_e32 v26, v43, v4
	v_fmac_f32_e32 v27, v44, v4
	v_fmac_f32_e32 v24, v45, v4
	v_fmac_f32_e32 v25, v58, v4
	v_fmac_f32_e32 v22, v48, v4
	v_fmac_f32_e32 v23, v50, v4
	v_fmac_f32_e32 v20, v50, v5
	v_fmac_f32_e32 v21, v50, v2
	v_fmac_f32_e32 v42, v50, v3
	s_waitcnt lgkmcnt(12)
	v_fmac_f32_e32 v66, v48, v73
	s_waitcnt vmcnt(1)
	v_fmac_f32_e32 v80, v49, v5
	v_fmac_f32_e32 v81, v51, v5
	v_fmac_f32_e32 v30, v47, v5
	v_fmac_f32_e32 v31, v53, v5
	v_fmac_f32_e32 v28, v59, v5
	v_fmac_f32_e32 v29, v62, v5
	v_fmac_f32_e32 v26, v46, v5
	v_fmac_f32_e32 v27, v43, v5
	v_fmac_f32_e32 v24, v44, v5
	v_fmac_f32_e32 v25, v45, v5
	v_fmac_f32_e32 v22, v58, v5
	v_fmac_f32_e32 v23, v48, v5
	v_fmac_f32_e32 v20, v48, v2
	v_fmac_f32_e32 v21, v48, v3
	v_fmac_f32_e32 v42, v48, v75
	s_waitcnt lgkmcnt(11)
	v_fmac_f32_e32 v66, v58, v72
	s_waitcnt vmcnt(0)
	v_fmac_f32_e32 v80, v55, v2
	v_fmac_f32_e32 v81, v49, v2
	v_fmac_f32_e32 v30, v51, v2
	v_fmac_f32_e32 v31, v47, v2
	v_fmac_f32_e32 v28, v53, v2
	v_fmac_f32_e32 v29, v59, v2
	v_fmac_f32_e32 v26, v62, v2
	v_fmac_f32_e32 v27, v46, v2
	v_fmac_f32_e32 v24, v43, v2
	v_fmac_f32_e32 v25, v44, v2
	v_fmac_f32_e32 v22, v45, v2
	v_fmac_f32_e32 v23, v58, v2
	v_fmac_f32_e32 v20, v58, v3
	v_fmac_f32_e32 v21, v58, v75
	v_fmac_f32_e32 v42, v58, v73
	v_and_b32_e32 v2, 64, v178
	s_waitcnt lgkmcnt(10)
; __device__ __forceinline__ void conv_task(const Params& p_, int l, int task, unsigned char* lds) {
;     ...
;       for (int j = 0; j < 46; ++j) { const float u = us[j * 512 + tid];
; #pragma unroll
;           for (int t = 0; t < 16; ++t) { const int k = j - t; if (k >= 0 && k < 31) y[t] += w[k] * u; } }
; #pragma unroll
;       for (int t = 0; t < 16; ++t) ys[t * 512 + tid] = y[t]; }
;     __syncthreads();
	v_fmac_f32_e32 v66, v45, v71
	v_fmac_f32_e32 v23, v45, v3
	v_fmac_f32_e32 v20, v45, v75
	v_fmac_f32_e32 v21, v45, v73
	v_fmac_f32_e32 v42, v45, v72
	v_add_u32_e32 v8, 64, v2
	v_xor_b32_e32 v2, 1, v178
	s_waitcnt lgkmcnt(9)
	v_fmac_f32_e32 v66, v44, v70
	v_fmac_f32_e32 v22, v44, v3
	v_fmac_f32_e32 v23, v44, v75
	v_fmac_f32_e32 v20, v44, v73
	v_fmac_f32_e32 v21, v44, v72
	v_fmac_f32_e32 v42, v44, v71
	v_cmp_lt_i32_e32 vcc, v2, v8
	s_waitcnt lgkmcnt(8)
	v_fmac_f32_e32 v66, v43, v69
	v_fmac_f32_e32 v25, v43, v3
	v_fmac_f32_e32 v22, v43, v75
	v_fmac_f32_e32 v23, v43, v73
	v_fmac_f32_e32 v20, v43, v72
	v_fmac_f32_e32 v21, v43, v71
	v_fmac_f32_e32 v42, v43, v70
	v_cndmask_b32_e32 v2, v178, v2, vcc
	s_waitcnt lgkmcnt(7)
	v_fmac_f32_e32 v66, v46, v68
	v_fmac_f32_e32 v24, v46, v3
	v_fmac_f32_e32 v25, v46, v75
	v_fmac_f32_e32 v22, v46, v73
	v_fmac_f32_e32 v23, v46, v72
	v_fmac_f32_e32 v20, v46, v71
	v_fmac_f32_e32 v21, v46, v70
	v_fmac_f32_e32 v42, v46, v69
	v_lshlrev_b32_e32 v39, 2, v2
	v_xor_b32_e32 v2, 2, v178
	s_waitcnt lgkmcnt(6)
	v_fmac_f32_e32 v66, v62, v67
	v_fmac_f32_e32 v27, v62, v3
	v_fmac_f32_e32 v24, v62, v75
	v_fmac_f32_e32 v25, v62, v73
	v_fmac_f32_e32 v22, v62, v72
	v_fmac_f32_e32 v23, v62, v71
	v_fmac_f32_e32 v20, v62, v70
	v_fmac_f32_e32 v21, v62, v69
	v_fmac_f32_e32 v42, v62, v68
	v_cmp_lt_i32_e32 vcc, v2, v8
	s_waitcnt lgkmcnt(5)
	v_fmac_f32_e32 v66, v59, v79
	v_fmac_f32_e32 v26, v59, v3
	v_fmac_f32_e32 v27, v59, v75
	v_fmac_f32_e32 v24, v59, v73
	v_fmac_f32_e32 v25, v59, v72
	v_fmac_f32_e32 v22, v59, v71
	v_fmac_f32_e32 v23, v59, v70
	v_fmac_f32_e32 v20, v59, v69
	v_fmac_f32_e32 v21, v59, v68
	v_fmac_f32_e32 v42, v59, v67
	v_cndmask_b32_e32 v2, v178, v2, vcc
	s_waitcnt lgkmcnt(4)
	v_fmac_f32_e32 v66, v53, v78
	v_fmac_f32_e32 v29, v53, v3
	v_fmac_f32_e32 v26, v53, v75
	v_fmac_f32_e32 v27, v53, v73
	v_fmac_f32_e32 v24, v53, v72
	v_fmac_f32_e32 v25, v53, v71
	v_fmac_f32_e32 v22, v53, v70
	v_fmac_f32_e32 v23, v53, v69
	v_fmac_f32_e32 v20, v53, v68
	v_fmac_f32_e32 v21, v53, v67
	v_fmac_f32_e32 v42, v53, v79
	v_lshlrev_b32_e32 v40, 2, v2
	v_xor_b32_e32 v2, 4, v178
	s_waitcnt lgkmcnt(3)
	v_fmac_f32_e32 v66, v47, v77
	v_fmac_f32_e32 v28, v47, v3
	v_fmac_f32_e32 v29, v47, v75
	v_fmac_f32_e32 v26, v47, v73
	v_fmac_f32_e32 v27, v47, v72
	v_fmac_f32_e32 v24, v47, v71
	v_fmac_f32_e32 v25, v47, v70
	v_fmac_f32_e32 v22, v47, v69
	v_fmac_f32_e32 v23, v47, v68
	v_fmac_f32_e32 v20, v47, v67
	v_fmac_f32_e32 v21, v47, v79
	v_fmac_f32_e32 v42, v47, v78
	v_cmp_lt_i32_e32 vcc, v2, v8
	s_waitcnt lgkmcnt(2)
	v_fmac_f32_e32 v66, v51, v76
	v_fmac_f32_e32 v31, v51, v3
	v_fmac_f32_e32 v28, v51, v75
	v_fmac_f32_e32 v29, v51, v73
	v_fmac_f32_e32 v26, v51, v72
	v_fmac_f32_e32 v27, v51, v71
	v_fmac_f32_e32 v24, v51, v70
	v_fmac_f32_e32 v25, v51, v69
	v_fmac_f32_e32 v22, v51, v68
	v_fmac_f32_e32 v23, v51, v67
	v_fmac_f32_e32 v20, v51, v79
	v_fmac_f32_e32 v21, v51, v78
	v_fmac_f32_e32 v42, v51, v77
	v_cndmask_b32_e32 v2, v178, v2, vcc
	s_waitcnt lgkmcnt(1)
	v_fmac_f32_e32 v66, v49, v74
	v_fmac_f32_e32 v81, v55, v3
	v_fmac_f32_e32 v30, v49, v3
	v_fmac_f32_e32 v31, v49, v75
	v_fmac_f32_e32 v28, v49, v73
	v_fmac_f32_e32 v29, v49, v72
	v_fmac_f32_e32 v26, v49, v71
	v_fmac_f32_e32 v27, v49, v70
	v_fmac_f32_e32 v24, v49, v69
	v_fmac_f32_e32 v25, v49, v68
	v_fmac_f32_e32 v22, v49, v67
	v_fmac_f32_e32 v23, v49, v79
	v_fmac_f32_e32 v20, v49, v78
	v_fmac_f32_e32 v21, v49, v77
	v_fmac_f32_e32 v42, v49, v76
	v_and_b32_e32 v38, 63, v54
	v_add_u32_e32 v0, s6, v60
	v_lshlrev_b32_e32 v41, 2, v2
	v_xor_b32_e32 v2, 8, v178
	s_waitcnt lgkmcnt(0)
	v_fmac_f32_e32 v66, v55, v82
	v_fmac_f32_e32 v30, v55, v75
	v_fmac_f32_e32 v31, v55, v73
	v_fmac_f32_e32 v28, v55, v72
	v_fmac_f32_e32 v29, v55, v71
	v_fmac_f32_e32 v26, v55, v70
	v_fmac_f32_e32 v27, v55, v69
	v_fmac_f32_e32 v24, v55, v68
	v_fmac_f32_e32 v25, v55, v67
	v_fmac_f32_e32 v22, v55, v79
	v_fmac_f32_e32 v23, v55, v78
	v_fmac_f32_e32 v20, v55, v77
	v_fmac_f32_e32 v21, v55, v76
	v_fmac_f32_e32 v42, v55, v74
	ds_write2st64_b32 v0, v80, v81 offset1:8
	ds_write2st64_b32 v0, v30, v31 offset0:16 offset1:24
	ds_write2st64_b32 v0, v28, v29 offset0:32 offset1:40
	ds_write2st64_b32 v0, v26, v27 offset0:48 offset1:56
	ds_write2st64_b32 v0, v24, v25 offset0:64 offset1:72
	ds_write2st64_b32 v0, v22, v23 offset0:80 offset1:88
	ds_write2st64_b32 v0, v20, v21 offset0:96 offset1:104
	ds_write2st64_b32 v0, v42, v66 offset0:112 offset1:120
	v_lshl_add_u32 v0, v38, 2, s6
	v_cmp_lt_i32_e32 vcc, v2, v8
	v_add_u32_e32 v43, 8, v56
	v_lshl_add_u32 v9, v56, 11, v0
	v_cndmask_b32_e32 v2, v178, v2, vcc
	v_lshl_add_u32 v0, v43, 11, v0
	s_waitcnt lgkmcnt(0)
	s_barrier
; __device__ __forceinline__ void conv_task(const Params& p_, int l, int task, unsigned char* lds) {
;     ...
;     for (int tw = 0; tw < 2; ++tw) { const int t = wave + 8 * tw; float v[8]; float s = 0.f;
; #pragma unroll
;         for (int j = 0; j < 8; ++j) { v[j] = ys[t * 512 + lane + 64 * j]; s += v[j]; }
;         const float mu = wave_sum(s) * (1.f / 512.f); float q = 0.f;
; #pragma unroll
;         for (int j = 0; j < 8; ++j) { v[j] -= mu; q += v[j] * v[j]; }
;         const float rstd = rsqrtf(wave_sum(q) * (1.f / 512.f) + 1e-6f);
	v_lshlrev_b32_e32 v42, 2, v2
	ds_read2st64_b32 v[2:3], v9 offset0:4 offset1:5
	ds_read2st64_b32 v[4:5], v9 offset1:1
	ds_read2st64_b32 v[6:7], v9 offset0:6 offset1:7
	ds_read2st64_b32 v[16:17], v9 offset0:2 offset1:3
	ds_read2st64_b32 v[10:11], v0 offset1:1
	ds_read2st64_b32 v[14:15], v0 offset0:2 offset1:3
	ds_read2st64_b32 v[18:19], v0 offset0:4 offset1:5
	ds_read2st64_b32 v[20:21], v0 offset0:6 offset1:7
	s_waitcnt lgkmcnt(6)
	v_mov_b32_e32 v23, v4
	v_mov_b32_e32 v9, v2
	s_waitcnt lgkmcnt(5)
	v_mov_b32_e32 v13, v6
	s_waitcnt lgkmcnt(3)
	v_mov_b32_e32 v22, v10
	v_pk_add_f32 v[24:25], v[22:23], 0 op_sel_hi:[1,0]
	v_mov_b32_e32 v4, v11
	v_pk_add_f32 v[10:11], v[24:25], v[4:5]
	s_waitcnt lgkmcnt(2)
	v_mov_b32_e32 v24, v14
	v_mov_b32_e32 v25, v16
	v_pk_add_f32 v[10:11], v[10:11], v[24:25]
	v_mov_b32_e32 v16, v15
	v_pk_add_f32 v[10:11], v[10:11], v[16:17]
	s_waitcnt lgkmcnt(1)
	v_mov_b32_e32 v14, v18
	v_mov_b32_e32 v15, v2
	v_pk_add_f32 v[10:11], v[10:11], v[14:15]
	v_mov_b32_e32 v2, v19
	v_pk_add_f32 v[10:11], v[10:11], v[2:3]
	s_waitcnt lgkmcnt(0)
	v_mov_b32_e32 v14, v20
	v_mov_b32_e32 v15, v6
	v_pk_add_f32 v[10:11], v[10:11], v[14:15]
	v_mov_b32_e32 v6, v21
	v_pk_add_f32 v[10:11], v[10:11], v[6:7]
	s_nop 1
	v_mov_b32_dpp v15, v11 quad_perm:[1,0,3,2] row_mask:0xf bank_mask:0xf
	v_mov_b32_dpp v14, v10 quad_perm:[1,0,3,2] row_mask:0xf bank_mask:0xf
	v_xor_b32_e32 v12, 16, v178
	v_cmp_lt_i32_e32 vcc, v12, v8
	v_mov_b32_e32 v30, v19
	v_mov_b32_e32 v31, v18
	s_waitcnt lgkmcnt(0)
	v_pk_add_f32 v[10:11], v[10:11], v[14:15]
	s_nop 1
	v_mov_b32_dpp v15, v11 quad_perm:[2,3,0,1] row_mask:0xf bank_mask:0xf
	v_mov_b32_dpp v14, v10 quad_perm:[2,3,0,1] row_mask:0xf bank_mask:0xf
	v_cndmask_b32_e32 v0, v178, v12, vcc
	v_lshlrev_b32_e32 v44, 2, v0
	v_xor_b32_e32 v0, 32, v178
	v_cmp_lt_i32_e32 vcc, v0, v8
	v_mov_b32_e32 v8, v3
	s_waitcnt lgkmcnt(0)
	v_pk_add_f32 v[2:3], v[10:11], v[14:15]
	s_nop 1
	v_mov_b32_dpp v11, v3 row_half_mirror row_mask:0xf bank_mask:0xf
	v_mov_b32_dpp v10, v2 row_half_mirror row_mask:0xf bank_mask:0xf
	v_cndmask_b32_e32 v0, v178, v0, vcc
	v_lshlrev_b32_e32 v45, 2, v0
	v_or_b32_e32 v0, s3, v38
	v_mov_b32_e32 v12, v7
	s_waitcnt lgkmcnt(0)
	v_pk_add_f32 v[2:3], v[2:3], v[10:11]
	s_nop 1
	v_mov_b32_dpp v11, v3 row_mirror row_mask:0xf bank_mask:0xf
	v_mov_b32_dpp v10, v2 row_mirror row_mask:0xf bank_mask:0xf
	v_lshlrev_b64 v[6:7], 2, v[0:1]
	v_lshl_add_u64 v[14:15], s[60:61], 0, v[6:7]
	v_lshl_add_u64 v[6:7], s[62:63], 0, v[6:7]
	global_load_dword v46, v[14:15], off
	global_load_dword v47, v[6:7], off
	s_waitcnt lgkmcnt(0)
	v_pk_add_f32 v[2:3], v[2:3], v[10:11]
	ds_bpermute_b32 v11, v44, v3
	ds_bpermute_b32 v10, v44, v2
	v_add_u32_e32 v6, s3, v38
	v_mov_b32_e32 v7, v1
	v_lshlrev_b64 v[6:7], 2, v[6:7]
	v_lshl_add_u64 v[26:27], s[60:61], 0, v[6:7]
	s_waitcnt lgkmcnt(0)
	v_pk_add_f32 v[2:3], v[2:3], v[10:11]
	ds_bpermute_b32 v11, v45, v3
	ds_bpermute_b32 v10, v45, v2
	global_load_dword v48, v[26:27], off offset:256
	v_lshl_add_u64 v[28:29], s[62:63], 0, v[6:7]
	global_load_dword v49, v[28:29], off offset:256
	s_waitcnt lgkmcnt(0)
	v_pk_add_f32 v[2:3], v[2:3], v[10:11]
	s_nop 0
	v_pk_mul_f32 v[18:19], v[2:3], s[2:3] op_sel_hi:[1,0]
	v_pk_fma_f32 v[10:11], v[2:3], s[2:3], v[4:5] op_sel_hi:[1,0,1] neg_lo:[1,0,0] neg_hi:[1,0,0]
	v_pk_add_f32 v[14:15], v[12:13], v[18:19] op_sel:[0,1] neg_lo:[0,1] neg_hi:[0,1]
	v_pk_fma_f32 v[12:13], v[2:3], s[2:3], v[22:23] op_sel_hi:[1,0,1] neg_lo:[1,0,0] neg_hi:[1,0,0]
	v_pk_mul_f32 v[4:5], v[10:11], v[10:11]
	v_pk_add_f32 v[32:33], v[8:9], v[18:19] op_sel:[0,1] neg_lo:[0,1] neg_hi:[0,1]
	v_pk_fma_f32 v[4:5], v[12:13], v[12:13], v[4:5]
	v_pk_fma_f32 v[8:9], v[2:3], s[2:3], v[24:25] op_sel_hi:[1,0,1] neg_lo:[1,0,0] neg_hi:[1,0,0]
	v_pk_fma_f32 v[6:7], v[2:3], s[2:3], v[16:17] op_sel_hi:[1,0,1] neg_lo:[1,0,0] neg_hi:[1,0,0]
	v_pk_fma_f32 v[4:5], v[8:9], v[8:9], v[4:5]
	v_pk_mul_f32 v[34:35], v[32:33], v[32:33]
	v_pk_fma_f32 v[2:3], v[6:7], v[6:7], v[4:5]
	v_pk_add_f32 v[4:5], v[30:31], v[18:19] op_sel_hi:[1,0] neg_lo:[0,1] neg_hi:[0,1]
	v_mov_b32_e32 v23, v35
	v_pk_mul_f32 v[16:17], v[4:5], v[4:5]
	v_pk_mul_f32 v[36:37], v[14:15], v[14:15]
	v_mov_b32_e32 v22, v17
	v_pk_add_f32 v[22:23], v[22:23], v[2:3]
	v_mov_b32_e32 v2, v21
	v_mov_b32_e32 v3, v20
	v_pk_add_f32 v[2:3], v[2:3], v[18:19] op_sel_hi:[1,0] neg_lo:[0,1] neg_hi:[0,1]
	v_mov_b32_e32 v17, v34
	v_pk_mul_f32 v[18:19], v[2:3], v[2:3]
	v_pk_add_f32 v[16:17], v[16:17], v[22:23]
	v_mov_b32_e32 v20, v19
	v_mov_b32_e32 v21, v37
	v_pk_add_f32 v[16:17], v[20:21], v[16:17]
	v_mov_b32_e32 v19, v36
	v_pk_add_f32 v[16:17], v[18:19], v[16:17]
	s_nop 1
	v_mov_b32_dpp v19, v17 quad_perm:[1,0,3,2] row_mask:0xf bank_mask:0xf
	v_mov_b32_dpp v18, v16 quad_perm:[1,0,3,2] row_mask:0xf bank_mask:0xf
	global_load_dword v22, v[26:27], off offset:512
	global_load_dword v23, v[28:29], off offset:512
	global_load_dword v24, v[26:27], off offset:768
	global_load_dword v25, v[28:29], off offset:768
	v_add_u32_e32 v20, s68, v56
	v_ashrrev_i32_e32 v21, 31, v20
	s_waitcnt lgkmcnt(0)
	v_pk_add_f32 v[16:17], v[16:17], v[18:19]
	s_nop 1
	v_mov_b32_dpp v19, v17 quad_perm:[2,3,0,1] row_mask:0xf bank_mask:0xf
	v_mov_b32_dpp v18, v16 quad_perm:[2,3,0,1] row_mask:0xf bank_mask:0xf
	v_lshlrev_b64 v[20:21], 10, v[20:21]
	v_lshl_add_u64 v[20:21], s[40:41], 0, v[20:21]
	s_waitcnt lgkmcnt(0)
	v_pk_add_f32 v[16:17], v[16:17], v[18:19]
	s_nop 1
	v_mov_b32_dpp v19, v17 row_half_mirror row_mask:0xf bank_mask:0xf
	v_mov_b32_dpp v18, v16 row_half_mirror row_mask:0xf bank_mask:0xf
	s_waitcnt lgkmcnt(0)
; __device__ __forceinline__ unsigned f2bf(float f) { unsigned u = __float_as_uint(f); return (u + 0x7fffu + ((u >> 16) & 1u)) >> 16; }
; __device__ __forceinline__ float silu_f(float v) { return v / (1.f + __expf(-v)); }
; __device__ __forceinline__ void conv_task(const Params& p_, int l, int task, unsigned char* lds) {
;     ...
;         const float mu = wave_sum(s) * (1.f / 512.f); float q = 0.f;
; #pragma unroll
;         for (int j = 0; j < 8; ++j) { v[j] -= mu; q += v[j] * v[j]; }
;         const float rstd = rsqrtf(wave_sum(q) * (1.f / 512.f) + 1e-6f);
;         bf16* orow = (bf16*)(p.ws + WS_CVH) + (size_t)(b * SEQ + t0 + t) * DG;
; #pragma unroll
;         for (int j = 0; j < 8; ++j) { const int ch = lane + 64 * j; const float y = v[j] * rstd * p.ln_g[l * DG + ch] + p.ln_b[l * DG + ch]; orow[ch] = (bf16)f2bf(silu_f(y)); } }
	v_pk_add_f32 v[16:17], v[16:17], v[18:19]
	s_nop 1
	v_mov_b32_dpp v19, v17 row_mirror row_mask:0xf bank_mask:0xf
	v_mov_b32_dpp v18, v16 row_mirror row_mask:0xf bank_mask:0xf
	s_waitcnt lgkmcnt(0)
	v_pk_add_f32 v[16:17], v[16:17], v[18:19]
	ds_bpermute_b32 v19, v44, v17
	ds_bpermute_b32 v18, v44, v16
	s_waitcnt lgkmcnt(0)
	v_pk_add_f32 v[16:17], v[16:17], v[18:19]
	ds_bpermute_b32 v19, v45, v17
	ds_bpermute_b32 v18, v45, v16
	s_waitcnt lgkmcnt(0)
	v_pk_add_f32 v[16:17], v[16:17], v[18:19]
	s_nop 0
	v_pk_fma_f32 v[16:17], v[16:17], s[2:3], v[146:147] op_sel_hi:[1,0,0]
	s_nop 0
	v_mul_f32_e32 v0, 0x4b800000, v17
	v_cmp_gt_f32_e32 vcc, s92, v17
	v_cmp_gt_f32_e64 s[36:37], s92, v16
	s_nop 0
	v_cndmask_b32_e32 v0, v17, v0, vcc
	v_rsq_f32_e32 v17, v0
	v_lshlrev_b32_e32 v0, 1, v38
	v_lshl_add_u64 v[18:19], v[20:21], 0, v[0:1]
	global_load_dword v20, v[28:29], off offset:1024
	global_load_dword v30, v[26:27], off offset:1024
	global_load_dword v31, v[26:27], off offset:1280
	global_load_dword v34, v[26:27], off offset:1536
	s_nop 0
	global_load_dword v26, v[26:27], off offset:1792
	v_mul_f32_e32 v21, 0x45800000, v17
	v_cndmask_b32_e32 v17, v17, v21, vcc
	v_mul_f32_e32 v13, v13, v17
	s_waitcnt vmcnt(11)
	v_fma_f32 v13, v46, v13, v47
	v_mul_f32_e32 v21, 0xbfb8aa3b, v13
	v_exp_f32_e32 v21, v21
	global_load_dword v36, v[28:29], off offset:1280
	global_load_dword v37, v[28:29], off offset:1536
	s_nop 0
	global_load_dword v28, v[28:29], off offset:1792
	v_mul_f32_e32 v11, v11, v17
	s_waitcnt vmcnt(12)
	v_fma_f32 v11, v48, v11, v49
	v_add_f32_e32 v21, 1.0, v21
	v_div_scale_f32 v27, s[12:13], v21, v21, v13
	v_rcp_f32_e32 v35, v27
	v_mul_f32_e32 v9, v9, v17
	v_mul_f32_e32 v7, v7, v17
	v_fma_f32 v29, -v27, v35, 1.0
	v_fmac_f32_e32 v35, v29, v35
	v_div_scale_f32 v29, vcc, v13, v21, v13
	v_mul_f32_e32 v38, v29, v35
	v_fma_f32 v39, -v27, v38, v29
	v_fmac_f32_e32 v38, v39, v35
	v_fma_f32 v27, -v27, v38, v29
	v_mul_f32_e32 v29, 0xbfb8aa3b, v11
	v_exp_f32_e32 v29, v29
	v_div_fmas_f32 v27, v27, v35, v38
	v_div_fixup_f32 v13, v27, v21, v13
	v_bfe_u32 v35, v13, 16, 1
	v_add_f32_e32 v21, 1.0, v29
	v_div_scale_f32 v27, s[12:13], v21, v21, v11
	v_rcp_f32_e32 v29, v27
	v_add3_u32 v13, v13, v35, s14
	global_store_short_d16_hi v[18:19], v13, off
	s_waitcnt vmcnt(11)
	v_fma_f32 v9, v22, v9, v23
	v_fma_f32 v13, -v27, v29, 1.0
	v_fmac_f32_e32 v29, v13, v29
	v_div_scale_f32 v13, vcc, v11, v21, v11
	v_mul_f32_e32 v35, v13, v29
	v_fma_f32 v38, -v27, v35, v13
	v_fmac_f32_e32 v35, v38, v29
	v_fma_f32 v13, -v27, v35, v13
	v_mul_f32_e32 v27, 0xbfb8aa3b, v9
	v_exp_f32_e32 v27, v27
	v_div_fmas_f32 v13, v13, v29, v35
	v_div_fixup_f32 v11, v13, v21, v11
	v_bfe_u32 v29, v11, 16, 1
	v_add_f32_e32 v13, 1.0, v27
	v_div_scale_f32 v21, s[12:13], v13, v13, v9
	v_rcp_f32_e32 v27, v21
	v_add3_u32 v11, v11, v29, s14
	global_store_short_d16_hi v[18:19], v11, off offset:128
	s_waitcnt vmcnt(10)
	v_fma_f32 v7, v24, v7, v25
	v_fma_f32 v11, -v21, v27, 1.0
	v_fmac_f32_e32 v27, v11, v27
	v_div_scale_f32 v11, vcc, v9, v13, v9
	v_mul_f32_e32 v29, v11, v27
	v_fma_f32 v35, -v21, v29, v11
	v_fmac_f32_e32 v29, v35, v27
	v_fma_f32 v11, -v21, v29, v11
	v_mul_f32_e32 v21, 0xbfb8aa3b, v7
	v_exp_f32_e32 v21, v21
	v_div_fmas_f32 v11, v11, v27, v29
	v_div_fixup_f32 v9, v11, v13, v9
	v_bfe_u32 v27, v9, 16, 1
	v_add_f32_e32 v11, 1.0, v21
	v_div_scale_f32 v13, s[12:13], v11, v11, v7
	v_rcp_f32_e32 v21, v13
	v_add3_u32 v9, v9, v27, s14
	global_store_short_d16_hi v[18:19], v9, off offset:256
	v_fma_f32 v9, -v13, v21, 1.0
	v_fmac_f32_e32 v21, v9, v21
	v_div_scale_f32 v9, vcc, v7, v11, v7
	v_mul_f32_e32 v27, v9, v21
	v_fma_f32 v29, -v13, v27, v9
	v_fmac_f32_e32 v27, v29, v21
	v_fma_f32 v9, -v13, v27, v9
	v_mul_f32_e32 v13, v33, v17
	s_waitcnt vmcnt(9)
	v_fma_f32 v13, v30, v13, v20
	v_mul_f32_e32 v29, 0xbfb8aa3b, v13
	v_exp_f32_e32 v29, v29
	v_div_fmas_f32 v9, v9, v21, v27
	v_div_fixup_f32 v7, v9, v11, v7
	v_bfe_u32 v27, v7, 16, 1
	v_add_f32_e32 v9, 1.0, v29
	v_div_scale_f32 v11, s[12:13], v9, v9, v13
	v_rcp_f32_e32 v21, v11
	v_add3_u32 v7, v7, v27, s14
	global_store_short_d16_hi v[18:19], v7, off offset:384
	v_fma_f32 v7, -v11, v21, 1.0
	v_fmac_f32_e32 v21, v7, v21
	v_div_scale_f32 v7, vcc, v13, v9, v13
	v_mul_f32_e32 v27, v7, v21
	v_fma_f32 v29, -v11, v27, v7
	v_fmac_f32_e32 v27, v29, v21
	v_fma_f32 v7, -v11, v27, v7
	v_mul_f32_e32 v11, v32, v17
	s_waitcnt vmcnt(6)
	v_fma_f32 v11, v31, v11, v36
	v_mul_f32_e32 v29, 0xbfb8aa3b, v11
	v_exp_f32_e32 v29, v29
	v_div_fmas_f32 v7, v7, v21, v27
	v_div_fixup_f32 v7, v7, v9, v13
	v_bfe_u32 v27, v7, 16, 1
	v_add_f32_e32 v9, 1.0, v29
	v_div_scale_f32 v13, s[12:13], v9, v9, v11
	v_rcp_f32_e32 v21, v13
	v_add3_u32 v7, v7, v27, s14
	global_store_short_d16_hi v[18:19], v7, off offset:512
	v_fma_f32 v7, -v13, v21, 1.0
	v_fmac_f32_e32 v21, v7, v21
	v_div_scale_f32 v7, vcc, v11, v9, v11
	v_mul_f32_e32 v27, v7, v21
	v_fma_f32 v29, -v13, v27, v7
	v_fmac_f32_e32 v27, v29, v21
	v_fma_f32 v7, -v13, v27, v7
	v_mul_f32_e32 v13, v15, v17
	s_waitcnt vmcnt(6)
	v_fma_f32 v13, v34, v13, v37
	v_mul_f32_e32 v15, 0xbfb8aa3b, v13
	v_exp_f32_e32 v15, v15
	v_div_fmas_f32 v7, v7, v21, v27
	v_div_fixup_f32 v7, v7, v9, v11
	v_bfe_u32 v21, v7, 16, 1
	v_add_f32_e32 v9, 1.0, v15
	v_div_scale_f32 v11, s[12:13], v9, v9, v13
	v_rcp_f32_e32 v15, v11
	v_add3_u32 v7, v7, v21, s14
	global_store_short_d16_hi v[18:19], v7, off offset:640
	v_fma_f32 v7, -v11, v15, 1.0
	v_fmac_f32_e32 v15, v7, v15
	v_div_scale_f32 v7, vcc, v13, v9, v13
	v_mul_f32_e32 v21, v7, v15
	v_fma_f32 v27, -v11, v21, v7
	v_fmac_f32_e32 v21, v27, v15
	v_fma_f32 v7, -v11, v21, v7
	v_mul_f32_e32 v11, v14, v17
	s_waitcnt vmcnt(6)
; __device__ __forceinline__ unsigned f2bf(float f) { unsigned u = __float_as_uint(f); return (u + 0x7fffu + ((u >> 16) & 1u)) >> 16; }
; __device__ __forceinline__ float silu_f(float v) { return v / (1.f + __expf(-v)); }
; __device__ __forceinline__ void conv_task(const Params& p_, int l, int task, unsigned char* lds) {
;     ...
;         const float rstd = rsqrtf(wave_sum(q) * (1.f / 512.f) + 1e-6f);
;         bf16* orow = (bf16*)(p.ws + WS_CVH) + (size_t)(b * SEQ + t0 + t) * DG;
; #pragma unroll
;         for (int j = 0; j < 8; ++j) { const int ch = lane + 64 * j; const float y = v[j] * rstd * p.ln_g[l * DG + ch] + p.ln_b[l * DG + ch]; orow[ch] = (bf16)f2bf(silu_f(y)); } }
;     __syncthreads();
	v_fma_f32 v11, v11, v26, v28
	v_mul_f32_e32 v14, 0xbfb8aa3b, v11
	v_exp_f32_e32 v14, v14
	v_div_fmas_f32 v7, v7, v15, v21
	v_div_fixup_f32 v7, v7, v9, v13
	v_bfe_u32 v15, v7, 16, 1
	v_add_f32_e32 v9, 1.0, v14
	v_div_scale_f32 v13, s[12:13], v9, v9, v11
	v_rcp_f32_e32 v14, v13
	v_add3_u32 v7, v7, v15, s14
	global_store_short_d16_hi v[18:19], v7, off offset:768
	v_fma_f32 v7, -v13, v14, 1.0
	v_fmac_f32_e32 v14, v7, v14
	v_div_scale_f32 v7, vcc, v11, v9, v11
	v_mul_f32_e32 v15, v7, v14
	v_fma_f32 v17, -v13, v15, v7
	v_fmac_f32_e32 v15, v17, v14
	v_fma_f32 v7, -v13, v15, v7
	v_mul_f32_e32 v13, 0x4b800000, v16
	v_cndmask_b32_e64 v13, v16, v13, s[36:37]
	v_rsq_f32_e32 v13, v13
	v_div_fmas_f32 v7, v7, v14, v15
	v_div_fixup_f32 v7, v7, v9, v11
	v_bfe_u32 v9, v7, 16, 1
	v_mul_f32_e32 v11, 0x45800000, v13
	v_cndmask_b32_e64 v14, v13, v11, s[36:37]
	v_mul_f32_e32 v11, v12, v14
	v_fmac_f32_e32 v47, v46, v11
	v_mul_f32_e32 v11, 0xbfb8aa3b, v47
	v_exp_f32_e32 v11, v11
	v_add3_u32 v7, v7, v9, s14
	global_store_short_d16_hi v[18:19], v7, off offset:896
	v_mul_f32_e32 v10, v10, v14
	v_add_f32_e32 v7, 1.0, v11
	v_div_scale_f32 v9, s[12:13], v7, v7, v47
	v_rcp_f32_e32 v11, v9
	v_fmac_f32_e32 v49, v48, v10
	v_mul_f32_e32 v10, 0xbfb8aa3b, v49
	v_exp_f32_e32 v10, v10
	v_fma_f32 v15, -v9, v11, 1.0
	v_fmac_f32_e32 v11, v15, v11
	v_div_scale_f32 v15, vcc, v47, v7, v47
	v_mul_f32_e32 v16, v15, v11
	v_fma_f32 v17, -v9, v16, v15
	v_fmac_f32_e32 v16, v17, v11
	v_fma_f32 v9, -v9, v16, v15
	v_add_f32_e32 v15, 1.0, v10
	v_div_fmas_f32 v9, v9, v11, v16
	v_div_scale_f32 v16, s[12:13], v15, v15, v49
	v_add_u32_e32 v12, s68, v43
	v_rcp_f32_e32 v17, v16
	v_ashrrev_i32_e32 v13, 31, v12
	v_lshlrev_b64 v[12:13], 10, v[12:13]
	v_lshl_add_u64 v[12:13], s[40:41], 0, v[12:13]
	v_div_fixup_f32 v7, v9, v7, v47
	v_mul_f32_e32 v8, v8, v14
	v_bfe_u32 v9, v7, 16, 1
	v_lshl_add_u64 v[10:11], v[12:13], 0, v[0:1]
	v_fma_f32 v0, -v16, v17, 1.0
	v_fmac_f32_e32 v23, v22, v8
	v_add3_u32 v7, v7, v9, s14
	v_fmac_f32_e32 v17, v0, v17
	v_div_scale_f32 v0, vcc, v49, v15, v49
	v_mul_f32_e32 v8, 0xbfb8aa3b, v23
	global_store_short_d16_hi v[10:11], v7, off
	v_mul_f32_e32 v7, v0, v17
	v_exp_f32_e32 v8, v8
	v_fma_f32 v9, -v16, v7, v0
	v_fmac_f32_e32 v7, v9, v17
	v_fma_f32 v0, -v16, v7, v0
	v_div_fmas_f32 v0, v0, v17, v7
	v_add_f32_e32 v7, 1.0, v8
	v_div_scale_f32 v8, s[12:13], v7, v7, v23
	v_rcp_f32_e32 v9, v8
	v_div_fixup_f32 v0, v0, v15, v49
	v_bfe_u32 v12, v0, 16, 1
	v_add3_u32 v0, v0, v12, s14
	v_mul_f32_e32 v6, v6, v14
	global_store_short_d16_hi v[10:11], v0, off offset:128
	v_fma_f32 v0, -v8, v9, 1.0
	v_fmac_f32_e32 v25, v24, v6
	v_fmac_f32_e32 v9, v0, v9
	v_div_scale_f32 v0, vcc, v23, v7, v23
	v_mul_f32_e32 v6, 0xbfb8aa3b, v25
	v_mul_f32_e32 v12, v0, v9
	v_exp_f32_e32 v6, v6
	v_fma_f32 v13, -v8, v12, v0
	v_fmac_f32_e32 v12, v13, v9
	v_fma_f32 v0, -v8, v12, v0
	v_div_fmas_f32 v0, v0, v9, v12
	v_add_f32_e32 v6, 1.0, v6
	v_div_fixup_f32 v0, v0, v7, v23
	v_div_scale_f32 v7, s[12:13], v6, v6, v25
	v_rcp_f32_e32 v8, v7
	v_bfe_u32 v9, v0, 16, 1
	v_add3_u32 v0, v0, v9, s14
	v_mul_f32_e32 v5, v5, v14
	global_store_short_d16_hi v[10:11], v0, off offset:256
	v_fma_f32 v0, -v7, v8, 1.0
	v_fmac_f32_e32 v20, v30, v5
	v_fmac_f32_e32 v8, v0, v8
	v_div_scale_f32 v0, vcc, v25, v6, v25
	v_mul_f32_e32 v5, 0xbfb8aa3b, v20
	v_mul_f32_e32 v9, v0, v8
	v_exp_f32_e32 v5, v5
	v_fma_f32 v12, -v7, v9, v0
	v_fmac_f32_e32 v9, v12, v8
	v_fma_f32 v0, -v7, v9, v0
	v_div_fmas_f32 v0, v0, v8, v9
	v_add_f32_e32 v5, 1.0, v5
	v_div_fixup_f32 v0, v0, v6, v25
	v_div_scale_f32 v6, s[12:13], v5, v5, v20
	v_rcp_f32_e32 v7, v6
	v_bfe_u32 v8, v0, 16, 1
	v_add3_u32 v0, v0, v8, s14
	v_mul_f32_e32 v4, v4, v14
	global_store_short_d16_hi v[10:11], v0, off offset:384
	v_fma_f32 v0, -v6, v7, 1.0
	v_fmac_f32_e32 v36, v31, v4
	v_fmac_f32_e32 v7, v0, v7
	v_div_scale_f32 v0, vcc, v20, v5, v20
	v_mul_f32_e32 v4, 0xbfb8aa3b, v36
	v_mul_f32_e32 v8, v0, v7
	v_exp_f32_e32 v4, v4
	v_fma_f32 v9, -v6, v8, v0
	v_fmac_f32_e32 v8, v9, v7
	v_fma_f32 v0, -v6, v8, v0
	v_div_fmas_f32 v0, v0, v7, v8
	v_add_f32_e32 v4, 1.0, v4
	v_div_fixup_f32 v0, v0, v5, v20
	v_div_scale_f32 v5, s[12:13], v4, v4, v36
	v_rcp_f32_e32 v6, v5
	v_bfe_u32 v7, v0, 16, 1
	v_add3_u32 v0, v0, v7, s14
	v_mul_f32_e32 v3, v3, v14
	global_store_short_d16_hi v[10:11], v0, off offset:512
	v_fma_f32 v0, -v5, v6, 1.0
	v_fmac_f32_e32 v37, v34, v3
	v_fmac_f32_e32 v6, v0, v6
	v_div_scale_f32 v0, vcc, v36, v4, v36
	v_mul_f32_e32 v3, 0xbfb8aa3b, v37
	v_mul_f32_e32 v7, v0, v6
	v_exp_f32_e32 v3, v3
	v_fma_f32 v8, -v5, v7, v0
	v_fmac_f32_e32 v7, v8, v6
	v_fma_f32 v0, -v5, v7, v0
	v_div_fmas_f32 v0, v0, v6, v7
	v_add_f32_e32 v3, 1.0, v3
	v_div_fixup_f32 v0, v0, v4, v36
	v_div_scale_f32 v4, s[12:13], v3, v3, v37
	v_rcp_f32_e32 v5, v4
	v_bfe_u32 v6, v0, 16, 1
	v_add3_u32 v0, v0, v6, s14
	v_mul_f32_e32 v2, v2, v14
	global_store_short_d16_hi v[10:11], v0, off offset:640
	v_fma_f32 v0, -v4, v5, 1.0
	v_fmac_f32_e32 v28, v26, v2
	v_fmac_f32_e32 v5, v0, v5
	v_div_scale_f32 v0, vcc, v37, v3, v37
	v_mul_f32_e32 v2, 0xbfb8aa3b, v28
	v_mul_f32_e32 v6, v0, v5
	v_exp_f32_e32 v2, v2
	v_fma_f32 v7, -v4, v6, v0
	v_fmac_f32_e32 v6, v7, v5
	v_fma_f32 v0, -v4, v6, v0
	v_div_fmas_f32 v0, v0, v5, v6
	v_add_f32_e32 v2, 1.0, v2
	v_div_fixup_f32 v0, v0, v3, v37
	v_div_scale_f32 v3, s[12:13], v2, v2, v28
	v_rcp_f32_e32 v4, v3
	v_bfe_u32 v5, v0, 16, 1
	v_add3_u32 v0, v0, v5, s14
	global_store_short_d16_hi v[10:11], v0, off offset:768
	v_fma_f32 v0, -v3, v4, 1.0
	v_fmac_f32_e32 v4, v0, v4
	v_div_scale_f32 v0, vcc, v28, v2, v28
	v_mul_f32_e32 v5, v0, v4
	v_fma_f32 v6, -v3, v5, v0
	v_fmac_f32_e32 v5, v6, v4
	v_fma_f32 v0, -v3, v5, v0
	v_div_fmas_f32 v0, v0, v4, v5
	v_div_fixup_f32 v0, v0, v2, v28
	v_bfe_u32 v2, v0, 16, 1
	v_add3_u32 v0, v0, v2, s14
	s_and_b64 vcc, exec, s[38:39]
	global_store_short_d16_hi v[10:11], v0, off offset:896
	s_barrier
	s_cbranch_vccnz .LBB0_451

; __device__ __forceinline__ int obid() { int b = (int)blockIdx.x; asm volatile("" : "+s"(b)); return b; }
; __device__ __forceinline__ void ph_final(const Params& p_) {
;     ...
;     for (int row = obid() * 8 + wave; row < MTOK; row += 2 * stride) {
;         const bool two = (row + stride < MTOK);
;         f32x4* xr0 = (f32x4*)(p.out + (size_t)row * DM) + lane; f32x4* xr1 = (f32x4*)(p.out + (size_t)(two ? row + stride : row) * DM) + lane;
;         f32x4 v0[8], v1[8], g4[8];
; #pragma unroll
;         for (int j = 0; j < 8; ++j) { v0[j] = xr0[64 * j]; v1[j] = xr1[64 * j]; g4[j] = *(const f32x4*)(p.final_g + (64 * j + lane) * 4); }
;         asm volatile("" ::: "memory");
;         float s0 = 0.f, s1 = 0.f;
; #pragma unroll
;         for (int j = 0; j < 8; ++j) { s0 += (v0[j][0] * v0[j][0] + v0[j][1] * v0[j][1]) + (v0[j][2] * v0[j][2] + v0[j][3] * v0[j][3]); s1 += (v1[j][0] * v1[j][0] + v1[j][1] * v1[j][1]) + (v1[j][2] * v1[j][2] + v1[j][3] * v1[j][3]); }
.LBB0_823:
	v_ashrrev_i32_e32 v1, 31, v0
	v_lshlrev_b64 v[2:3], 13, v[0:1]
	v_lshl_add_u64 v[112:113], v[96:97], 0, v[2:3]
	v_add_co_u32_e32 v4, vcc, s17, v112
	v_add_u32_e32 v124, s94, v0
	s_nop 0
	v_addc_co_u32_e32 v5, vcc, 0, v113, vcc
	v_cmp_gt_i32_e32 vcc, s15, v124
	global_load_dwordx4 v[92:95], v[112:113], off
	global_load_dwordx4 v[72:75], v[112:113], off offset:1024
	global_load_dwordx4 v[68:71], v[112:113], off offset:2048
	global_load_dwordx4 v[48:51], v[112:113], off offset:3072
	v_cndmask_b32_e32 v0, v0, v124, vcc
	v_ashrrev_i32_e32 v1, 31, v0
	v_lshlrev_b64 v[0:1], 13, v[0:1]
	v_lshl_add_u64 v[110:111], v[96:97], 0, v[0:1]
	global_load_dwordx4 v[44:47], v[4:5], off
	global_load_dwordx4 v[84:87], v[110:111], off
	global_load_dwordx4 v[80:83], v[110:111], off offset:1024
	global_load_dwordx4 v[60:63], v[110:111], off offset:2048
	v_add_co_u32_e32 v6, vcc, s17, v110
	s_waitcnt vmcnt(0)
	v_mov_b32_e32 v116, v93
	v_addc_co_u32_e32 v7, vcc, 0, v111, vcc
	global_load_dwordx4 v[36:39], v[6:7], off
	global_load_dwordx4 v[56:59], v[110:111], off offset:3072
	global_load_dwordx4 v[88:91], v[98:99], off
	global_load_dwordx4 v[76:79], v[98:99], off offset:1024
	global_load_dwordx4 v[64:67], v[98:99], off offset:2048
	global_load_dwordx4 v[52:55], v[98:99], off offset:3072
	global_load_dwordx4 v[28:31], v[4:5], off offset:1024
	global_load_dwordx4 v[40:43], v[100:101], off
	global_load_dwordx4 v[24:27], v[102:103], off
	global_load_dwordx4 v[12:15], v[104:105], off
	global_load_dwordx4 v[0:3], v[106:107], off
	global_load_dwordx4 v[32:35], v[6:7], off offset:1024
	global_load_dwordx4 v[20:23], v[4:5], off offset:2048
	global_load_dwordx4 v[8:11], v[4:5], off offset:3072
	global_load_dwordx4 v[16:19], v[6:7], off offset:2048
	s_nop 0
	global_load_dwordx4 v[4:7], v[6:7], off offset:3072
	v_mov_b32_e32 v117, v73
	v_mov_b32_e32 v128, v95
	v_mov_b32_e32 v129, v75
	v_mov_b32_e32 v114, v92
	v_mov_b32_e32 v115, v72
	v_mov_b32_e32 v126, v94
	v_mov_b32_e32 v127, v74
	v_pk_mul_f32 v[116:117], v[116:117], v[116:117]
	v_pk_mul_f32 v[128:129], v[128:129], v[128:129]
	v_pk_mul_f32 v[130:131], v[70:71], v[70:71]
	v_pk_mul_f32 v[132:133], v[68:69], v[68:69]
	v_mul_f32_e32 v134, v49, v49
	v_pk_fma_f32 v[114:115], v[114:115], v[114:115], v[116:117]
	v_pk_fma_f32 v[116:117], v[126:127], v[126:127], v[128:129]
	v_mov_b32_e32 v128, v85
	v_mov_b32_e32 v129, v81
	v_mov_b32_e32 v140, v87
	v_mov_b32_e32 v141, v83
	v_pk_mov_b32 v[138:139], v[132:133], v[130:131] op_sel:[1,0]
	v_mov_b32_e32 v133, v131
	v_pk_fma_f32 v[130:131], v[48:49], v[48:49], v[134:135] op_sel_hi:[1,1,0]
	v_mov_b32_e32 v126, v84
	v_mov_b32_e32 v127, v80
	v_mov_b32_e32 v134, v86
	v_mov_b32_e32 v135, v82
	v_pk_add_f32 v[114:115], v[114:115], v[116:117]
	v_pk_mul_f32 v[116:117], v[128:129], v[128:129]
	v_pk_mul_f32 v[128:129], v[140:141], v[140:141]
	v_mul_f32_e32 v136, v51, v51
	v_mul_f32_e32 v137, v45, v45
	v_pk_add_f32 v[132:133], v[138:139], v[132:133]
	v_pk_fma_f32 v[116:117], v[126:127], v[126:127], v[116:117]
	v_pk_fma_f32 v[126:127], v[134:135], v[134:135], v[128:129]
	v_mul_f32_e32 v125, v44, v44
	v_mul_f32_e32 v144, v46, v46
	v_mul_f32_e32 v145, v47, v47
	v_pk_mul_f32 v[138:139], v[62:63], v[62:63]
	v_pk_mul_f32 v[142:143], v[60:61], v[60:61]
	v_pk_add_f32 v[132:133], v[132:133], v[132:133] op_sel:[0,1] op_sel_hi:[1,0]
	v_pk_add_f32 v[114:115], v[114:115], v[114:115] op_sel:[0,1] op_sel_hi:[1,0]
	v_pk_add_f32 v[116:117], v[116:117], v[126:127]
	v_pk_fma_f32 v[126:127], v[50:51], v[50:51], v[136:137] op_sel_hi:[1,1,0]
	v_mov_b32_e32 v131, v144
	v_pk_mov_b32 v[140:141], v[142:143], v[138:139] op_sel:[1,0]
	v_mov_b32_e32 v143, v139
	v_mov_b32_e32 v133, v137
	v_mov_b32_e32 v115, v125
	v_mov_b32_e32 v127, v145
	v_pk_add_f32 v[128:129], v[140:141], v[142:143]
	v_pk_add_f32 v[114:115], v[114:115], v[132:133]
	v_pk_add_f32 v[126:127], v[130:131], v[126:127]
	v_pk_add_f32 v[116:117], v[116:117], v[116:117] op_sel:[0,1] op_sel_hi:[1,0]
	v_pk_add_f32 v[114:115], v[114:115], v[126:127]
	v_pk_add_f32 v[126:127], v[128:129], v[128:129] op_sel:[0,1] op_sel_hi:[1,0]
	v_pk_add_f32 v[114:115], v[114:115], v[114:115] op_sel:[0,1] op_sel_hi:[1,0]
	v_cmp_lt_i32_e32 vcc, v118, v109
	s_waitcnt vmcnt(15)
	v_mul_f32_e32 v125, v36, v36
	v_mul_f32_e32 v130, v37, v37
	v_mov_b32_e32 v117, v125
	v_mov_b32_e32 v127, v130
	v_pk_add_f32 v[116:117], v[116:117], v[126:127]
	s_waitcnt vmcnt(14)
	v_mul_f32_e32 v126, v57, v57
	v_mul_f32_e32 v128, v59, v59
	v_mul_f32_e32 v131, v38, v38
	v_mul_f32_e32 v132, v39, v39
	v_pk_fma_f32 v[126:127], v[56:57], v[56:57], v[126:127] op_sel_hi:[1,1,0]
	v_pk_fma_f32 v[128:129], v[58:59], v[58:59], v[128:129] op_sel_hi:[1,1,0]
	v_mov_b32_e32 v127, v131
	v_mov_b32_e32 v129, v132
	v_pk_add_f32 v[126:127], v[126:127], v[128:129]
	s_waitcnt vmcnt(9)
; __device__ __forceinline__ void ph_final(const Params& p_) {
;     ...
;         for (int j = 0; j < 8; ++j) { s0 += (v0[j][0] * v0[j][0] + v0[j][1] * v0[j][1]) + (v0[j][2] * v0[j][2] + v0[j][3] * v0[j][3]); s1 += (v1[j][0] * v1[j][0] + v1[j][1] * v1[j][1]) + (v1[j][2] * v1[j][2] + v1[j][3] * v1[j][3]); }
;         s0 = wave_sum(s0); s1 = wave_sum(s1);
;         const float r0 = rsqrtf(s0 * (1.f / DM) + 1e-6f), r1 = rsqrtf(s1 * (1.f / DM) + 1e-6f);
; #pragma unroll
;         for (int j = 0; j < 8; ++j) { xr0[64 * j] = v0[j] * r0 * g4[j]; if (two) xr1[64 * j] = v1[j] * r1 * g4[j]; }
	v_pk_mul_f32 v[128:129], v[28:29], v[28:29]
	v_pk_add_f32 v[116:117], v[116:117], v[126:127]
	v_pk_mul_f32 v[126:127], v[30:31], v[30:31]
	s_waitcnt vmcnt(2)
	v_mul_f32_e32 v125, v8, v8
	v_pk_mov_b32 v[130:131], v[128:129], v[126:127] op_sel:[1,0]
	v_mov_b32_e32 v129, v127
	v_pk_add_f32 v[126:127], v[130:131], v[128:129]
	v_pk_mul_f32 v[128:129], v[34:35], v[34:35]
	v_pk_mul_f32 v[130:131], v[32:33], v[32:33]
	v_pk_add_f32 v[126:127], v[126:127], v[126:127] op_sel:[0,1] op_sel_hi:[1,0]
	v_pk_mov_b32 v[132:133], v[130:131], v[128:129] op_sel:[1,0]
	v_mov_b32_e32 v131, v129
	v_pk_add_f32 v[128:129], v[132:133], v[130:131]
	v_mul_f32_e32 v130, v9, v9
	v_mov_b32_e32 v115, v125
	v_mov_b32_e32 v127, v130
	v_pk_add_f32 v[114:115], v[114:115], v[126:127]
	v_mul_f32_e32 v126, v21, v21
	v_mul_f32_e32 v131, v10, v10
	v_pk_fma_f32 v[126:127], v[20:21], v[20:21], v[126:127] op_sel_hi:[1,1,0]
	v_mul_f32_e32 v130, v23, v23
	v_mul_f32_e32 v132, v11, v11
	v_mov_b32_e32 v127, v131
	v_pk_fma_f32 v[130:131], v[22:23], v[22:23], v[130:131] op_sel_hi:[1,1,0]
	s_waitcnt vmcnt(0)
	v_mul_f32_e32 v125, v4, v4
	v_mov_b32_e32 v131, v132
	v_pk_add_f32 v[126:127], v[126:127], v[130:131]
	v_mul_f32_e32 v130, v5, v5
	v_pk_add_f32 v[114:115], v[114:115], v[126:127]
	v_pk_add_f32 v[116:117], v[116:117], v[116:117] op_sel:[0,1] op_sel_hi:[1,0]
	v_pk_add_f32 v[126:127], v[128:129], v[128:129] op_sel:[0,1] op_sel_hi:[1,0]
	v_mov_b32_e32 v117, v125
	v_mov_b32_e32 v127, v130
	v_pk_add_f32 v[116:117], v[116:117], v[126:127]
	v_mul_f32_e32 v126, v17, v17
	v_mul_f32_e32 v128, v19, v19
	v_mul_f32_e32 v131, v6, v6
	v_mul_f32_e32 v132, v7, v7
	v_pk_fma_f32 v[126:127], v[16:17], v[16:17], v[126:127] op_sel_hi:[1,1,0]
	v_pk_fma_f32 v[128:129], v[18:19], v[18:19], v[128:129] op_sel_hi:[1,1,0]
	v_mov_b32_e32 v127, v131
	v_mov_b32_e32 v129, v132
	v_pk_add_f32 v[126:127], v[126:127], v[128:129]
	v_cndmask_b32_e32 v125, v178, v118, vcc
	v_pk_add_f32 v[116:117], v[116:117], v[126:127]
	v_mov_b32_e32 v127, v114
	v_mov_b32_e32 v126, v116
	v_mov_b32_e32 v114, v117
	v_lshlrev_b32_e32 v125, 2, v125
	v_pk_add_f32 v[114:115], v[126:127], v[114:115]
	s_nop 1
	v_mov_b32_dpp v117, v115 quad_perm:[1,0,3,2] row_mask:0xf bank_mask:0xf
	v_mov_b32_dpp v116, v114 quad_perm:[1,0,3,2] row_mask:0xf bank_mask:0xf
	v_cmp_lt_i32_e32 vcc, v119, v109
	s_waitcnt lgkmcnt(0)
	v_pk_add_f32 v[114:115], v[114:115], v[116:117]
	v_cndmask_b32_e32 v125, v178, v119, vcc
	v_lshlrev_b32_e32 v125, 2, v125
	s_nop 1
	v_mov_b32_dpp v117, v115 quad_perm:[2,3,0,1] row_mask:0xf bank_mask:0xf
	v_mov_b32_dpp v116, v114 quad_perm:[2,3,0,1] row_mask:0xf bank_mask:0xf
	v_cmp_lt_i32_e32 vcc, v120, v109
	s_waitcnt lgkmcnt(0)
	v_pk_add_f32 v[114:115], v[114:115], v[116:117]
	v_cndmask_b32_e32 v125, v178, v120, vcc
	v_lshlrev_b32_e32 v125, 2, v125
	s_nop 1
	v_mov_b32_dpp v117, v115 row_half_mirror row_mask:0xf bank_mask:0xf
	v_mov_b32_dpp v116, v114 row_half_mirror row_mask:0xf bank_mask:0xf
	v_cmp_lt_i32_e32 vcc, v121, v109
	s_waitcnt lgkmcnt(0)
	v_pk_add_f32 v[114:115], v[114:115], v[116:117]
	v_cndmask_b32_e32 v125, v178, v121, vcc
	v_lshlrev_b32_e32 v125, 2, v125
	s_nop 1
	v_mov_b32_dpp v117, v115 row_mirror row_mask:0xf bank_mask:0xf
	v_mov_b32_dpp v116, v114 row_mirror row_mask:0xf bank_mask:0xf
	v_cmp_lt_i32_e32 vcc, v122, v109
	s_waitcnt lgkmcnt(0)
	v_pk_add_f32 v[114:115], v[114:115], v[116:117]
	v_cndmask_b32_e32 v125, v178, v122, vcc
	v_lshlrev_b32_e32 v125, 2, v125
	ds_bpermute_b32 v117, v125, v115
	ds_bpermute_b32 v116, v125, v114
	v_cmp_lt_i32_e32 vcc, v123, v109
	s_waitcnt lgkmcnt(0)
	v_pk_add_f32 v[114:115], v[114:115], v[116:117]
	v_cndmask_b32_e32 v125, v178, v123, vcc
	v_lshlrev_b32_e32 v125, 2, v125
	ds_bpermute_b32 v117, v125, v115
	ds_bpermute_b32 v116, v125, v114
	v_cmp_lt_i32_e32 vcc, s16, v124
	s_waitcnt lgkmcnt(0)
	v_pk_add_f32 v[114:115], v[114:115], v[116:117]
	s_nop 0
	v_pk_fma_f32 v[116:117], v[114:115], s[14:15], v[108:109] op_sel_hi:[1,0,0]
	s_nop 0
	v_mul_f32_e32 v114, 0x4b800000, v117
	v_cmp_gt_f32_e64 s[2:3], s18, v117
	v_cmp_gt_f32_e64 s[0:1], s18, v116
	s_nop 0
	v_cndmask_b32_e64 v114, v117, v114, s[2:3]
	v_rsq_f32_e32 v114, v114
	s_nop 0
	v_mul_f32_e32 v115, 0x45800000, v114
	v_cndmask_b32_e64 v114, v114, v115, s[2:3]
	v_mov_b32_e32 v115, v114
	v_pk_mul_f32 v[92:93], v[92:93], v[114:115] op_sel_hi:[1,0]
	v_pk_mul_f32 v[94:95], v[94:95], v[114:115] op_sel_hi:[1,0]
	v_pk_mul_f32 v[92:93], v[88:89], v[92:93]
	v_pk_mul_f32 v[94:95], v[90:91], v[94:95]
	global_store_dwordx4 v[112:113], v[92:95], off
	s_nop 1
	v_pk_mul_f32 v[92:93], v[72:73], v[114:115]
	s_and_saveexec_b64 s[2:3], vcc
	s_xor_b64 s[2:3], exec, s[2:3]
	s_cbranch_execz .LBB0_825
	v_mov_b32_e32 v72, v114
	v_mov_b32_e32 v73, v114
	v_pk_mul_f32 v[72:73], v[74:75], v[72:73]
	s_nop 0
	v_pk_mul_f32 v[74:75], v[78:79], v[72:73]
	v_pk_mul_f32 v[72:73], v[76:77], v[92:93]
	global_store_dwordx4 v[112:113], v[72:75], off offset:1024
